# prompt indexer top-k: new register-resident per-wave selection fast path (row in VGPRs, DPP reductions, float-threshold mask pass, writelane mask words); original path kept as fallback
# speedup vs baseline: 1.0413x; 1.0413x over previous
; #define SMF_FOR(...) { _Pragma("unroll 4") for (int j = 0; j < R - 1; ++j) { const int key = 64 * j + lane; const float v = row[key]; (void)key; __VA_ARGS__ } \
;                        { const int key = 64 * (R - 1) + lane; if (key < nv) { const float v = row[key]; __VA_ARGS__ } } }
; __device__ __forceinline__ bool select_mask_fast(const LAS float* row, int nv, int ksel, LAS unsigned* scr, int lane, u64& word_o) {
;     ...
;     const int R = (nv + 63) >> 6;
;     ...
;     float m0 = -INFINITY, m1 = -INFINITY, m2 = -INFINITY, m3 = -INFINITY;
;     SMF_FOR({ const float n1 = __builtin_amdgcn_fmed3f(m0, m1, v), n2 = __builtin_amdgcn_fmed3f(m1, m2, v), n3 = __builtin_amdgcn_fmed3f(m2, m3, v); m0 = __builtin_amdgcn_fmed3f(m0, v, BIGF); m1 = n1; m2 = n2; m3 = n3; })
;     const float lo = wave_min(m3), hi = wave_max(m0);
; __device__ __forceinline__ void idx_topk_phase(const IdxArgs& a, LAS unsigned char* lds_sc, LAS unsigned char* lds_scr, int G, int tid) {
;     ...
;             { const int t = t0 + wave, nv = t + 1; u64 myword = 0ull;
;               if (nv <= KSEL_P) { const int lo64 = 64 * lane; myword = (lo64 + 63 <= t) ? ~0ull : (lo64 <= t ? ((1ull << (t - lo64 + 1)) - 1ull) : 0ull); }
;               else if (select_mask_fast(SC + wave * SEQ, nv, KSEL_P, scr, lane, myword)) { }
.LBB0_742:
	s_add_i32 s52, s8, s2
	s_cmpk_gt_i32 s52, 0xff
	s_mov_b64 s[0:1], -1
	s_waitcnt lgkmcnt(0)
	s_barrier
	s_cbranch_scc0 .LBB0_984
	s_add_i32 s70, s52, 64
	s_lshr_b32 s70, s70, 6
	s_add_i32 s71, s70, -1
	s_lshr_b32 s71, s71, 2
	v_sub_u32_e32 v126, s52, v135
	v_ashrrev_i32_e32 v126, 6, v126
	v_mov_b32_e32 v127, 0xff800000
	v_mov_b32_e32 v114, 0xff800000
	v_mov_b32_e32 v115, 0xff800000
	v_mov_b32_e32 v116, 0xff800000
	v_mov_b32_e32 v117, 0xff800000
	v_mov_b32_e32 v144, 0
	v_mov_b32_e32 v145, 0
	ds_read2st64_b32 v[2:3], v146 offset0:0 offset1:1
	ds_read2st64_b32 v[4:5], v146 offset0:2 offset1:3
	ds_read2st64_b32 v[6:7], v146 offset0:4 offset1:5
	ds_read2st64_b32 v[8:9], v146 offset0:6 offset1:7
	ds_read2st64_b32 v[10:11], v146 offset0:8 offset1:9
	ds_read2st64_b32 v[12:13], v146 offset0:10 offset1:11
	s_waitcnt lgkmcnt(4)
	s_cmp_eq_u32 s71, 0
	s_cbranch_scc1 .Lnsel_fix_0
.Lnsel_fixed_0:
	v_med3_f32 v117, v116, v117, v2
	v_med3_f32 v116, v115, v116, v2
	v_med3_f32 v115, v114, v115, v2
	v_med3_f32 v114, v114, v2, s89
	v_med3_f32 v117, v116, v117, v3
	v_med3_f32 v116, v115, v116, v3
	v_med3_f32 v115, v114, v115, v3
	v_med3_f32 v114, v114, v3, s89
	v_med3_f32 v117, v116, v117, v4
	v_med3_f32 v116, v115, v116, v4
	v_med3_f32 v115, v114, v115, v4
	v_med3_f32 v114, v114, v4, s89
	v_med3_f32 v117, v116, v117, v5
	v_med3_f32 v116, v115, v116, v5
	v_med3_f32 v115, v114, v115, v5
	v_med3_f32 v114, v114, v5, s89
	s_cmp_le_u32 s70, 4
	s_cbranch_scc1 .Lnsel_p1done
	ds_read2st64_b32 v[14:15], v146 offset0:12 offset1:13
	ds_read2st64_b32 v[16:17], v146 offset0:14 offset1:15
	s_waitcnt lgkmcnt(4)
	s_cmp_eq_u32 s71, 1
	s_cbranch_scc1 .Lnsel_fix_1
.Lnsel_fixed_1:
	v_med3_f32 v117, v116, v117, v6
	v_med3_f32 v116, v115, v116, v6
	v_med3_f32 v115, v114, v115, v6
	v_med3_f32 v114, v114, v6, s89
	v_med3_f32 v117, v116, v117, v7
	v_med3_f32 v116, v115, v116, v7
	v_med3_f32 v115, v114, v115, v7
	v_med3_f32 v114, v114, v7, s89
	v_med3_f32 v117, v116, v117, v8
	v_med3_f32 v116, v115, v116, v8
	v_med3_f32 v115, v114, v115, v8
	v_med3_f32 v114, v114, v8, s89
	v_med3_f32 v117, v116, v117, v9
	v_med3_f32 v116, v115, v116, v9
	v_med3_f32 v115, v114, v115, v9
	v_med3_f32 v114, v114, v9, s89
	s_cmp_le_u32 s70, 8
	s_cbranch_scc1 .Lnsel_p1done
	ds_read2st64_b32 v[18:19], v146 offset0:16 offset1:17
	ds_read2st64_b32 v[20:21], v146 offset0:18 offset1:19
	s_waitcnt lgkmcnt(4)
	s_cmp_eq_u32 s71, 2
	s_cbranch_scc1 .Lnsel_fix_2
.Lnsel_fixed_2:
	v_max3_f32 v118, v10, v11, v12
	v_max_f32_e32 v118, v118, v13
	v_med3_f32 v117, v116, v117, v118
	v_med3_f32 v116, v115, v116, v118
	v_med3_f32 v115, v114, v115, v118
	v_med3_f32 v114, v114, v118, s89
	s_cmp_le_u32 s70, 12
	s_cbranch_scc1 .Lnsel_p1done
	ds_read2st64_b32 v[22:23], v146 offset0:20 offset1:21
	ds_read2st64_b32 v[24:25], v146 offset0:22 offset1:23
	s_waitcnt lgkmcnt(4)
	s_cmp_eq_u32 s71, 3
	s_cbranch_scc1 .Lnsel_fix_3
.Lnsel_fixed_3:
	v_max3_f32 v118, v14, v15, v16
	v_max_f32_e32 v118, v118, v17
	v_med3_f32 v117, v116, v117, v118
	v_med3_f32 v116, v115, v116, v118
	v_med3_f32 v115, v114, v115, v118
	v_med3_f32 v114, v114, v118, s89
	s_cmp_le_u32 s70, 16
	s_cbranch_scc1 .Lnsel_p1done
	ds_read2st64_b32 v[26:27], v146 offset0:24 offset1:25
	ds_read2st64_b32 v[28:29], v146 offset0:26 offset1:27
	s_waitcnt lgkmcnt(4)
	s_cmp_eq_u32 s71, 4
	s_cbranch_scc1 .Lnsel_fix_4
.Lnsel_fixed_4:
	v_max3_f32 v118, v18, v19, v20
	v_max_f32_e32 v118, v118, v21
	v_med3_f32 v117, v116, v117, v118
	v_med3_f32 v116, v115, v116, v118
	v_med3_f32 v115, v114, v115, v118
	v_med3_f32 v114, v114, v118, s89
	s_cmp_le_u32 s70, 20
	s_cbranch_scc1 .Lnsel_p1done
	ds_read2st64_b32 v[30:31], v146 offset0:28 offset1:29
	ds_read2st64_b32 v[32:33], v146 offset0:30 offset1:31
	s_waitcnt lgkmcnt(4)
	s_cmp_eq_u32 s71, 5
	s_cbranch_scc1 .Lnsel_fix_5
.Lnsel_fixed_5:
	v_max3_f32 v118, v22, v23, v24
	v_max_f32_e32 v118, v118, v25
	v_med3_f32 v117, v116, v117, v118
	v_med3_f32 v116, v115, v116, v118
	v_med3_f32 v115, v114, v115, v118
	v_med3_f32 v114, v114, v118, s89
	s_cmp_le_u32 s70, 24
	s_cbranch_scc1 .Lnsel_p1done
	ds_read2st64_b32 v[34:35], v146 offset0:32 offset1:33
	ds_read2st64_b32 v[36:37], v146 offset0:34 offset1:35
	s_waitcnt lgkmcnt(4)
	s_cmp_eq_u32 s71, 6
	s_cbranch_scc1 .Lnsel_fix_6
.Lnsel_fixed_6:
	v_max3_f32 v118, v26, v27, v28
	v_max_f32_e32 v118, v118, v29
	v_med3_f32 v117, v116, v117, v118
	v_med3_f32 v116, v115, v116, v118
	v_med3_f32 v115, v114, v115, v118
	v_med3_f32 v114, v114, v118, s89
	s_cmp_le_u32 s70, 28
	s_cbranch_scc1 .Lnsel_p1done
	ds_read2st64_b32 v[38:39], v146 offset0:36 offset1:37
	ds_read2st64_b32 v[40:41], v146 offset0:38 offset1:39
	s_waitcnt lgkmcnt(4)
	s_cmp_eq_u32 s71, 7
	s_cbranch_scc1 .Lnsel_fix_7
.Lnsel_fixed_7:
	v_max3_f32 v118, v30, v31, v32
	v_max_f32_e32 v118, v118, v33
	v_med3_f32 v117, v116, v117, v118
	v_med3_f32 v116, v115, v116, v118
	v_med3_f32 v115, v114, v115, v118
	v_med3_f32 v114, v114, v118, s89
	s_cmp_le_u32 s70, 32
	s_cbranch_scc1 .Lnsel_p1done
	ds_read2st64_b32 v[42:43], v146 offset0:40 offset1:41
	ds_read2st64_b32 v[44:45], v146 offset0:42 offset1:43
	s_waitcnt lgkmcnt(4)
	s_cmp_eq_u32 s71, 8
	s_cbranch_scc1 .Lnsel_fix_8
.Lnsel_fixed_8:
	v_max3_f32 v118, v34, v35, v36
	v_max_f32_e32 v118, v118, v37
	v_med3_f32 v117, v116, v117, v118
	v_med3_f32 v116, v115, v116, v118
	v_med3_f32 v115, v114, v115, v118
	v_med3_f32 v114, v114, v118, s89
	s_cmp_le_u32 s70, 36
	s_cbranch_scc1 .Lnsel_p1done
	ds_read2st64_b32 v[46:47], v146 offset0:44 offset1:45
	ds_read2st64_b32 v[48:49], v146 offset0:46 offset1:47
	s_waitcnt lgkmcnt(4)
	s_cmp_eq_u32 s71, 9
	s_cbranch_scc1 .Lnsel_fix_9
; #define DSA_LWAIT() asm volatile("s_waitcnt lgkmcnt(0)" ::: "memory")
; #define SMF_FOR(...) { _Pragma("unroll 4") for (int j = 0; j < R - 1; ++j) { const int key = 64 * j + lane; const float v = row[key]; (void)key; __VA_ARGS__ } \
;                        { const int key = 64 * (R - 1) + lane; if (key < nv) { const float v = row[key]; __VA_ARGS__ } } }
; __device__ __forceinline__ bool select_mask_fast(const LAS float* row, int nv, int ksel, LAS unsigned* scr, int lane, u64& word_o) {
;     ...
;     SMF_FOR({ const float n1 = __builtin_amdgcn_fmed3f(m0, m1, v), n2 = __builtin_amdgcn_fmed3f(m1, m2, v), n3 = __builtin_amdgcn_fmed3f(m2, m3, v); m0 = __builtin_amdgcn_fmed3f(m0, v, BIGF); m1 = n1; m2 = n2; m3 = n3; })
;     const float lo = wave_min(m3), hi = wave_max(m0);
;     if (ksel > 256 || !(lo > -INFINITY) || !(hi - lo > 1e-30f)) return false;
;     const float scale = 256.0f / (hi - lo), nls = -lo * scale;
; #pragma unroll
;     for (int k = 0; k < 4; ++k) hist[4 * lane + k] = 0u;
;     if (lane == 0) cnt[0] = 0u;
;     DSA_LWAIT();
;     SMF_FOR({ if (v >= lo) { int bin = (int)fmaf(v, scale, nls); bin = bin > 255 ? 255 : bin; bin = bin < 0 ? 0 : bin; __hip_atomic_fetch_add(&hist[bin], 1u, __ATOMIC_RELAXED, __HIP_MEMORY_SCOPE_WORKGROUP); } })
.Lnsel_fixed_9:
	v_max3_f32 v118, v38, v39, v40
	v_max_f32_e32 v118, v118, v41
	v_med3_f32 v117, v116, v117, v118
	v_med3_f32 v116, v115, v116, v118
	v_med3_f32 v115, v114, v115, v118
	v_med3_f32 v114, v114, v118, s89
	s_cmp_le_u32 s70, 40
	s_cbranch_scc1 .Lnsel_p1done
	ds_read2st64_b32 v[50:51], v146 offset0:48 offset1:49
	ds_read2st64_b32 v[52:53], v146 offset0:50 offset1:51
	s_waitcnt lgkmcnt(4)
	s_cmp_eq_u32 s71, 10
	s_cbranch_scc1 .Lnsel_fix_10
.Lnsel_fixed_10:
	v_max3_f32 v118, v42, v43, v44
	v_max_f32_e32 v118, v118, v45
	v_med3_f32 v117, v116, v117, v118
	v_med3_f32 v116, v115, v116, v118
	v_med3_f32 v115, v114, v115, v118
	v_med3_f32 v114, v114, v118, s89
	s_cmp_le_u32 s70, 44
	s_cbranch_scc1 .Lnsel_p1done
	ds_read2st64_b32 v[54:55], v146 offset0:52 offset1:53
	ds_read2st64_b32 v[56:57], v146 offset0:54 offset1:55
	s_waitcnt lgkmcnt(4)
	s_cmp_eq_u32 s71, 11
	s_cbranch_scc1 .Lnsel_fix_11
.Lnsel_fixed_11:
	v_max3_f32 v118, v46, v47, v48
	v_max_f32_e32 v118, v118, v49
	v_med3_f32 v117, v116, v117, v118
	v_med3_f32 v116, v115, v116, v118
	v_med3_f32 v115, v114, v115, v118
	v_med3_f32 v114, v114, v118, s89
	s_cmp_le_u32 s70, 48
	s_cbranch_scc1 .Lnsel_p1done
	ds_read2st64_b32 v[58:59], v146 offset0:56 offset1:57
	ds_read2st64_b32 v[60:61], v146 offset0:58 offset1:59
	s_waitcnt lgkmcnt(4)
	s_cmp_eq_u32 s71, 12
	s_cbranch_scc1 .Lnsel_fix_12
.Lnsel_fixed_12:
	v_max3_f32 v118, v50, v51, v52
	v_max_f32_e32 v118, v118, v53
	v_med3_f32 v117, v116, v117, v118
	v_med3_f32 v116, v115, v116, v118
	v_med3_f32 v115, v114, v115, v118
	v_med3_f32 v114, v114, v118, s89
	s_cmp_le_u32 s70, 52
	s_cbranch_scc1 .Lnsel_p1done
	ds_read2st64_b32 v[62:63], v146 offset0:60 offset1:61
	ds_read2st64_b32 v[64:65], v146 offset0:62 offset1:63
	s_waitcnt lgkmcnt(4)
	s_cmp_eq_u32 s71, 13
	s_cbranch_scc1 .Lnsel_fix_13
.Lnsel_fixed_13:
	v_max3_f32 v118, v54, v55, v56
	v_max_f32_e32 v118, v118, v57
	v_med3_f32 v117, v116, v117, v118
	v_med3_f32 v116, v115, v116, v118
	v_med3_f32 v115, v114, v115, v118
	v_med3_f32 v114, v114, v118, s89
	s_cmp_le_u32 s70, 56
	s_cbranch_scc1 .Lnsel_p1done
	s_waitcnt lgkmcnt(2)
	s_cmp_eq_u32 s71, 14
	s_cbranch_scc1 .Lnsel_fix_14
.Lnsel_fixed_14:
	v_max3_f32 v118, v58, v59, v60
	v_max_f32_e32 v118, v118, v61
	v_med3_f32 v117, v116, v117, v118
	v_med3_f32 v116, v115, v116, v118
	v_med3_f32 v115, v114, v115, v118
	v_med3_f32 v114, v114, v118, s89
	s_cmp_le_u32 s70, 60
	s_cbranch_scc1 .Lnsel_p1done
	s_waitcnt lgkmcnt(0)
	s_cmp_eq_u32 s71, 15
	s_cbranch_scc1 .Lnsel_fix_15
.Lnsel_fixed_15:
	v_max3_f32 v118, v62, v63, v64
	v_max_f32_e32 v118, v118, v65
	v_med3_f32 v117, v116, v117, v118
	v_med3_f32 v116, v115, v116, v118
	v_med3_f32 v115, v114, v115, v118
	v_med3_f32 v114, v114, v118, s89
.Lnsel_p1done:
	s_nop 1
	v_max_f32_dpp v114, v114, v114 quad_perm:[1,0,3,2] row_mask:0xf bank_mask:0xf
	v_min_f32_dpp v117, v117, v117 quad_perm:[1,0,3,2] row_mask:0xf bank_mask:0xf
	s_nop 1
	v_max_f32_dpp v114, v114, v114 quad_perm:[2,3,0,1] row_mask:0xf bank_mask:0xf
	v_min_f32_dpp v117, v117, v117 quad_perm:[2,3,0,1] row_mask:0xf bank_mask:0xf
	s_nop 1
	v_max_f32_dpp v114, v114, v114 row_half_mirror row_mask:0xf bank_mask:0xf
	v_min_f32_dpp v117, v117, v117 row_half_mirror row_mask:0xf bank_mask:0xf
	s_nop 1
	v_max_f32_dpp v114, v114, v114 row_mirror row_mask:0xf bank_mask:0xf
	v_min_f32_dpp v117, v117, v117 row_mirror row_mask:0xf bank_mask:0xf
	s_nop 1
	v_max_f32_dpp v114, v114, v114 row_bcast:15 row_mask:0xa bank_mask:0xf
	v_min_f32_dpp v117, v117, v117 row_bcast:15 row_mask:0xa bank_mask:0xf
	s_nop 1
	v_max_f32_dpp v114, v114, v114 row_bcast:31 row_mask:0xc bank_mask:0xf
	v_min_f32_dpp v117, v117, v117 row_bcast:31 row_mask:0xc bank_mask:0xf
	s_nop 1
	v_readlane_b32 s73, v114, 63
	v_readlane_b32 s72, v117, 63
	s_nop 1
	v_mov_b32_e32 v130, s72
	v_sub_f32_e32 v131, s73, v130
	v_cmp_lg_f32_e32 vcc, s90, v130
	s_mov_b64 s[78:79], vcc
	v_cmp_lt_f32_e32 vcc, s91, v131
	s_and_b64 vcc, vcc, s[78:79]
	v_rcp_f32_e32 v128, v131
	s_cbranch_vccz .Lnsel_bail
	v_mul_f32_e32 v128, 0x43800000, v128
	v_mul_f32_e64 v129, v128, -v130
	ds_write_b128 v147, v[216:219]
	s_waitcnt lgkmcnt(0)
	v_cmp_le_f32_e64 s[78:79], s72, v2
	v_cmp_le_f32_e64 s[80:81], s72, v3
	v_cmp_le_f32_e64 s[82:83], s72, v4
	v_cmp_le_f32_e64 s[84:85], s72, v5
	v_fma_f32 v2, v2, v128, v129
	v_fma_f32 v3, v3, v128, v129
	v_fma_f32 v4, v4, v128, v129
	v_fma_f32 v5, v5, v128, v129
	v_cvt_i32_f32_e32 v122, v2
	v_cvt_i32_f32_e32 v123, v3
	v_cvt_i32_f32_e32 v124, v4
	v_cvt_i32_f32_e32 v125, v5
	v_med3_i32 v122, v122, 0, v243
	v_med3_i32 v123, v123, 0, v243
	v_med3_i32 v124, v124, 0, v243
	v_med3_i32 v125, v125, 0, v243
	v_lshl_add_u32 v122, v122, 2, s10
	v_lshl_add_u32 v123, v123, 2, s10
	v_lshl_add_u32 v124, v124, 2, s10
	v_lshl_add_u32 v125, v125, 2, s10
	s_mov_b64 exec, s[78:79]
	ds_add_u32 v122, v239
	s_mov_b64 exec, s[80:81]
	ds_add_u32 v123, v239
	s_mov_b64 exec, s[82:83]
	ds_add_u32 v124, v239
	s_mov_b64 exec, s[84:85]
	ds_add_u32 v125, v239
	s_mov_b64 exec, -1
	s_cmp_le_u32 s70, 4
	s_cbranch_scc1 .Lnsel_histdone
	v_cmp_le_f32_e64 s[78:79], s72, v6
	v_cmp_le_f32_e64 s[80:81], s72, v7
	v_cmp_le_f32_e64 s[82:83], s72, v8
	v_cmp_le_f32_e64 s[84:85], s72, v9
	v_fma_f32 v6, v6, v128, v129
	v_fma_f32 v7, v7, v128, v129
	v_fma_f32 v8, v8, v128, v129
	v_fma_f32 v9, v9, v128, v129
	v_cvt_i32_f32_e32 v122, v6
	v_cvt_i32_f32_e32 v123, v7
	v_cvt_i32_f32_e32 v124, v8
	v_cvt_i32_f32_e32 v125, v9
	v_med3_i32 v122, v122, 0, v243
	v_med3_i32 v123, v123, 0, v243
	v_med3_i32 v124, v124, 0, v243
	v_med3_i32 v125, v125, 0, v243
	v_lshl_add_u32 v122, v122, 2, s10
	v_lshl_add_u32 v123, v123, 2, s10
	v_lshl_add_u32 v124, v124, 2, s10
	v_lshl_add_u32 v125, v125, 2, s10
	s_mov_b64 exec, s[78:79]
	ds_add_u32 v122, v239
	s_mov_b64 exec, s[80:81]
	ds_add_u32 v123, v239
	s_mov_b64 exec, s[82:83]
	ds_add_u32 v124, v239
	s_mov_b64 exec, s[84:85]
	ds_add_u32 v125, v239
	s_mov_b64 exec, -1
	s_cmp_le_u32 s70, 8
	s_cbranch_scc1 .Lnsel_histdone
; #define DSA_LWAIT() asm volatile("s_waitcnt lgkmcnt(0)" ::: "memory")
; #define SMF_FOR(...) { _Pragma("unroll 4") for (int j = 0; j < R - 1; ++j) { const int key = 64 * j + lane; const float v = row[key]; (void)key; __VA_ARGS__ } \
;                        { const int key = 64 * (R - 1) + lane; if (key < nv) { const float v = row[key]; __VA_ARGS__ } } }
; __device__ __forceinline__ bool select_mask_fast(const LAS float* row, int nv, int ksel, LAS unsigned* scr, int lane, u64& word_o) {
;     ...
; #pragma unroll
;     for (int k = 0; k < 4; ++k) hist[4 * lane + k] = 0u;
;     if (lane == 0) cnt[0] = 0u;
;     DSA_LWAIT();
;     SMF_FOR({ if (v >= lo) { int bin = (int)fmaf(v, scale, nls); bin = bin > 255 ? 255 : bin; bin = bin < 0 ? 0 : bin; __hip_atomic_fetch_add(&hist[bin], 1u, __ATOMIC_RELAXED, __HIP_MEMORY_SCOPE_WORKGROUP); } })
	v_cmp_le_f32_e64 s[78:79], s72, v10
	v_cmp_le_f32_e64 s[80:81], s72, v11
	v_cmp_le_f32_e64 s[82:83], s72, v12
	v_cmp_le_f32_e64 s[84:85], s72, v13
	v_fma_f32 v10, v10, v128, v129
	v_fma_f32 v11, v11, v128, v129
	v_fma_f32 v12, v12, v128, v129
	v_fma_f32 v13, v13, v128, v129
	v_cvt_i32_f32_e32 v122, v10
	v_cvt_i32_f32_e32 v123, v11
	v_cvt_i32_f32_e32 v124, v12
	v_cvt_i32_f32_e32 v125, v13
	v_med3_i32 v122, v122, 0, v243
	v_med3_i32 v123, v123, 0, v243
	v_med3_i32 v124, v124, 0, v243
	v_med3_i32 v125, v125, 0, v243
	v_lshl_add_u32 v122, v122, 2, s10
	v_lshl_add_u32 v123, v123, 2, s10
	v_lshl_add_u32 v124, v124, 2, s10
	v_lshl_add_u32 v125, v125, 2, s10
	s_mov_b64 exec, s[78:79]
	ds_add_u32 v122, v239
	s_mov_b64 exec, s[80:81]
	ds_add_u32 v123, v239
	s_mov_b64 exec, s[82:83]
	ds_add_u32 v124, v239
	s_mov_b64 exec, s[84:85]
	ds_add_u32 v125, v239
	s_mov_b64 exec, -1
	s_cmp_le_u32 s70, 12
	s_cbranch_scc1 .Lnsel_histdone
	v_cmp_le_f32_e64 s[78:79], s72, v14
	v_cmp_le_f32_e64 s[80:81], s72, v15
	v_cmp_le_f32_e64 s[82:83], s72, v16
	v_cmp_le_f32_e64 s[84:85], s72, v17
	v_fma_f32 v14, v14, v128, v129
	v_fma_f32 v15, v15, v128, v129
	v_fma_f32 v16, v16, v128, v129
	v_fma_f32 v17, v17, v128, v129
	v_cvt_i32_f32_e32 v122, v14
	v_cvt_i32_f32_e32 v123, v15
	v_cvt_i32_f32_e32 v124, v16
	v_cvt_i32_f32_e32 v125, v17
	v_med3_i32 v122, v122, 0, v243
	v_med3_i32 v123, v123, 0, v243
	v_med3_i32 v124, v124, 0, v243
	v_med3_i32 v125, v125, 0, v243
	v_lshl_add_u32 v122, v122, 2, s10
	v_lshl_add_u32 v123, v123, 2, s10
	v_lshl_add_u32 v124, v124, 2, s10
	v_lshl_add_u32 v125, v125, 2, s10
	s_mov_b64 exec, s[78:79]
	ds_add_u32 v122, v239
	s_mov_b64 exec, s[80:81]
	ds_add_u32 v123, v239
	s_mov_b64 exec, s[82:83]
	ds_add_u32 v124, v239
	s_mov_b64 exec, s[84:85]
	ds_add_u32 v125, v239
	s_mov_b64 exec, -1
	s_cmp_le_u32 s70, 16
	s_cbranch_scc1 .Lnsel_histdone
	v_cmp_le_f32_e64 s[78:79], s72, v18
	v_cmp_le_f32_e64 s[80:81], s72, v19
	v_cmp_le_f32_e64 s[82:83], s72, v20
	v_cmp_le_f32_e64 s[84:85], s72, v21
	v_fma_f32 v18, v18, v128, v129
	v_fma_f32 v19, v19, v128, v129
	v_fma_f32 v20, v20, v128, v129
	v_fma_f32 v21, v21, v128, v129
	v_cvt_i32_f32_e32 v122, v18
	v_cvt_i32_f32_e32 v123, v19
	v_cvt_i32_f32_e32 v124, v20
	v_cvt_i32_f32_e32 v125, v21
	v_med3_i32 v122, v122, 0, v243
	v_med3_i32 v123, v123, 0, v243
	v_med3_i32 v124, v124, 0, v243
	v_med3_i32 v125, v125, 0, v243
	v_lshl_add_u32 v122, v122, 2, s10
	v_lshl_add_u32 v123, v123, 2, s10
	v_lshl_add_u32 v124, v124, 2, s10
	v_lshl_add_u32 v125, v125, 2, s10
	s_mov_b64 exec, s[78:79]
	ds_add_u32 v122, v239
	s_mov_b64 exec, s[80:81]
	ds_add_u32 v123, v239
	s_mov_b64 exec, s[82:83]
	ds_add_u32 v124, v239
	s_mov_b64 exec, s[84:85]
	ds_add_u32 v125, v239
	s_mov_b64 exec, -1
	s_cmp_le_u32 s70, 20
	s_cbranch_scc1 .Lnsel_histdone
	v_cmp_le_f32_e64 s[78:79], s72, v22
	v_cmp_le_f32_e64 s[80:81], s72, v23
	v_cmp_le_f32_e64 s[82:83], s72, v24
	v_cmp_le_f32_e64 s[84:85], s72, v25
	v_fma_f32 v22, v22, v128, v129
	v_fma_f32 v23, v23, v128, v129
	v_fma_f32 v24, v24, v128, v129
	v_fma_f32 v25, v25, v128, v129
	v_cvt_i32_f32_e32 v122, v22
	v_cvt_i32_f32_e32 v123, v23
	v_cvt_i32_f32_e32 v124, v24
	v_cvt_i32_f32_e32 v125, v25
	v_med3_i32 v122, v122, 0, v243
	v_med3_i32 v123, v123, 0, v243
	v_med3_i32 v124, v124, 0, v243
	v_med3_i32 v125, v125, 0, v243
	v_lshl_add_u32 v122, v122, 2, s10
	v_lshl_add_u32 v123, v123, 2, s10
	v_lshl_add_u32 v124, v124, 2, s10
	v_lshl_add_u32 v125, v125, 2, s10
	s_mov_b64 exec, s[78:79]
	ds_add_u32 v122, v239
	s_mov_b64 exec, s[80:81]
	ds_add_u32 v123, v239
	s_mov_b64 exec, s[82:83]
	ds_add_u32 v124, v239
	s_mov_b64 exec, s[84:85]
	ds_add_u32 v125, v239
	s_mov_b64 exec, -1
	s_cmp_le_u32 s70, 24
	s_cbranch_scc1 .Lnsel_histdone
	v_cmp_le_f32_e64 s[78:79], s72, v26
	v_cmp_le_f32_e64 s[80:81], s72, v27
	v_cmp_le_f32_e64 s[82:83], s72, v28
	v_cmp_le_f32_e64 s[84:85], s72, v29
	v_fma_f32 v26, v26, v128, v129
	v_fma_f32 v27, v27, v128, v129
	v_fma_f32 v28, v28, v128, v129
	v_fma_f32 v29, v29, v128, v129
	v_cvt_i32_f32_e32 v122, v26
	v_cvt_i32_f32_e32 v123, v27
	v_cvt_i32_f32_e32 v124, v28
	v_cvt_i32_f32_e32 v125, v29
	v_med3_i32 v122, v122, 0, v243
	v_med3_i32 v123, v123, 0, v243
	v_med3_i32 v124, v124, 0, v243
	v_med3_i32 v125, v125, 0, v243
	v_lshl_add_u32 v122, v122, 2, s10
	v_lshl_add_u32 v123, v123, 2, s10
	v_lshl_add_u32 v124, v124, 2, s10
	v_lshl_add_u32 v125, v125, 2, s10
	s_mov_b64 exec, s[78:79]
	ds_add_u32 v122, v239
	s_mov_b64 exec, s[80:81]
	ds_add_u32 v123, v239
	s_mov_b64 exec, s[82:83]
	ds_add_u32 v124, v239
	s_mov_b64 exec, s[84:85]
	ds_add_u32 v125, v239
	s_mov_b64 exec, -1
	s_cmp_le_u32 s70, 28
	s_cbranch_scc1 .Lnsel_histdone
	v_cmp_le_f32_e64 s[78:79], s72, v30
	v_cmp_le_f32_e64 s[80:81], s72, v31
	v_cmp_le_f32_e64 s[82:83], s72, v32
	v_cmp_le_f32_e64 s[84:85], s72, v33
	v_fma_f32 v30, v30, v128, v129
	v_fma_f32 v31, v31, v128, v129
	v_fma_f32 v32, v32, v128, v129
	v_fma_f32 v33, v33, v128, v129
	v_cvt_i32_f32_e32 v122, v30
	v_cvt_i32_f32_e32 v123, v31
	v_cvt_i32_f32_e32 v124, v32
	v_cvt_i32_f32_e32 v125, v33
	v_med3_i32 v122, v122, 0, v243
	v_med3_i32 v123, v123, 0, v243
	v_med3_i32 v124, v124, 0, v243
	v_med3_i32 v125, v125, 0, v243
	v_lshl_add_u32 v122, v122, 2, s10
	v_lshl_add_u32 v123, v123, 2, s10
	v_lshl_add_u32 v124, v124, 2, s10
	v_lshl_add_u32 v125, v125, 2, s10
	s_mov_b64 exec, s[78:79]
	ds_add_u32 v122, v239
	s_mov_b64 exec, s[80:81]
	ds_add_u32 v123, v239
	s_mov_b64 exec, s[82:83]
	ds_add_u32 v124, v239
	s_mov_b64 exec, s[84:85]
	ds_add_u32 v125, v239
	s_mov_b64 exec, -1
	s_cmp_le_u32 s70, 32
	s_cbranch_scc1 .Lnsel_histdone
; #define DSA_LWAIT() asm volatile("s_waitcnt lgkmcnt(0)" ::: "memory")
; #define SMF_FOR(...) { _Pragma("unroll 4") for (int j = 0; j < R - 1; ++j) { const int key = 64 * j + lane; const float v = row[key]; (void)key; __VA_ARGS__ } \
;                        { const int key = 64 * (R - 1) + lane; if (key < nv) { const float v = row[key]; __VA_ARGS__ } } }
; __device__ __forceinline__ bool select_mask_fast(const LAS float* row, int nv, int ksel, LAS unsigned* scr, int lane, u64& word_o) {
;     ...
; #pragma unroll
;     for (int k = 0; k < 4; ++k) hist[4 * lane + k] = 0u;
;     if (lane == 0) cnt[0] = 0u;
;     DSA_LWAIT();
;     SMF_FOR({ if (v >= lo) { int bin = (int)fmaf(v, scale, nls); bin = bin > 255 ? 255 : bin; bin = bin < 0 ? 0 : bin; __hip_atomic_fetch_add(&hist[bin], 1u, __ATOMIC_RELAXED, __HIP_MEMORY_SCOPE_WORKGROUP); } })
	v_cmp_le_f32_e64 s[78:79], s72, v34
	v_cmp_le_f32_e64 s[80:81], s72, v35
	v_cmp_le_f32_e64 s[82:83], s72, v36
	v_cmp_le_f32_e64 s[84:85], s72, v37
	v_fma_f32 v34, v34, v128, v129
	v_fma_f32 v35, v35, v128, v129
	v_fma_f32 v36, v36, v128, v129
	v_fma_f32 v37, v37, v128, v129
	v_cvt_i32_f32_e32 v122, v34
	v_cvt_i32_f32_e32 v123, v35
	v_cvt_i32_f32_e32 v124, v36
	v_cvt_i32_f32_e32 v125, v37
	v_med3_i32 v122, v122, 0, v243
	v_med3_i32 v123, v123, 0, v243
	v_med3_i32 v124, v124, 0, v243
	v_med3_i32 v125, v125, 0, v243
	v_lshl_add_u32 v122, v122, 2, s10
	v_lshl_add_u32 v123, v123, 2, s10
	v_lshl_add_u32 v124, v124, 2, s10
	v_lshl_add_u32 v125, v125, 2, s10
	s_mov_b64 exec, s[78:79]
	ds_add_u32 v122, v239
	s_mov_b64 exec, s[80:81]
	ds_add_u32 v123, v239
	s_mov_b64 exec, s[82:83]
	ds_add_u32 v124, v239
	s_mov_b64 exec, s[84:85]
	ds_add_u32 v125, v239
	s_mov_b64 exec, -1
	s_cmp_le_u32 s70, 36
	s_cbranch_scc1 .Lnsel_histdone
	v_cmp_le_f32_e64 s[78:79], s72, v38
	v_cmp_le_f32_e64 s[80:81], s72, v39
	v_cmp_le_f32_e64 s[82:83], s72, v40
	v_cmp_le_f32_e64 s[84:85], s72, v41
	v_fma_f32 v38, v38, v128, v129
	v_fma_f32 v39, v39, v128, v129
	v_fma_f32 v40, v40, v128, v129
	v_fma_f32 v41, v41, v128, v129
	v_cvt_i32_f32_e32 v122, v38
	v_cvt_i32_f32_e32 v123, v39
	v_cvt_i32_f32_e32 v124, v40
	v_cvt_i32_f32_e32 v125, v41
	v_med3_i32 v122, v122, 0, v243
	v_med3_i32 v123, v123, 0, v243
	v_med3_i32 v124, v124, 0, v243
	v_med3_i32 v125, v125, 0, v243
	v_lshl_add_u32 v122, v122, 2, s10
	v_lshl_add_u32 v123, v123, 2, s10
	v_lshl_add_u32 v124, v124, 2, s10
	v_lshl_add_u32 v125, v125, 2, s10
	s_mov_b64 exec, s[78:79]
	ds_add_u32 v122, v239
	s_mov_b64 exec, s[80:81]
	ds_add_u32 v123, v239
	s_mov_b64 exec, s[82:83]
	ds_add_u32 v124, v239
	s_mov_b64 exec, s[84:85]
	ds_add_u32 v125, v239
	s_mov_b64 exec, -1
	s_cmp_le_u32 s70, 40
	s_cbranch_scc1 .Lnsel_histdone
	v_cmp_le_f32_e64 s[78:79], s72, v42
	v_cmp_le_f32_e64 s[80:81], s72, v43
	v_cmp_le_f32_e64 s[82:83], s72, v44
	v_cmp_le_f32_e64 s[84:85], s72, v45
	v_fma_f32 v42, v42, v128, v129
	v_fma_f32 v43, v43, v128, v129
	v_fma_f32 v44, v44, v128, v129
	v_fma_f32 v45, v45, v128, v129
	v_cvt_i32_f32_e32 v122, v42
	v_cvt_i32_f32_e32 v123, v43
	v_cvt_i32_f32_e32 v124, v44
	v_cvt_i32_f32_e32 v125, v45
	v_med3_i32 v122, v122, 0, v243
	v_med3_i32 v123, v123, 0, v243
	v_med3_i32 v124, v124, 0, v243
	v_med3_i32 v125, v125, 0, v243
	v_lshl_add_u32 v122, v122, 2, s10
	v_lshl_add_u32 v123, v123, 2, s10
	v_lshl_add_u32 v124, v124, 2, s10
	v_lshl_add_u32 v125, v125, 2, s10
	s_mov_b64 exec, s[78:79]
	ds_add_u32 v122, v239
	s_mov_b64 exec, s[80:81]
	ds_add_u32 v123, v239
	s_mov_b64 exec, s[82:83]
	ds_add_u32 v124, v239
	s_mov_b64 exec, s[84:85]
	ds_add_u32 v125, v239
	s_mov_b64 exec, -1
	s_cmp_le_u32 s70, 44
	s_cbranch_scc1 .Lnsel_histdone
	v_cmp_le_f32_e64 s[78:79], s72, v46
	v_cmp_le_f32_e64 s[80:81], s72, v47
	v_cmp_le_f32_e64 s[82:83], s72, v48
	v_cmp_le_f32_e64 s[84:85], s72, v49
	v_fma_f32 v46, v46, v128, v129
	v_fma_f32 v47, v47, v128, v129
	v_fma_f32 v48, v48, v128, v129
	v_fma_f32 v49, v49, v128, v129
	v_cvt_i32_f32_e32 v122, v46
	v_cvt_i32_f32_e32 v123, v47
	v_cvt_i32_f32_e32 v124, v48
	v_cvt_i32_f32_e32 v125, v49
	v_med3_i32 v122, v122, 0, v243
	v_med3_i32 v123, v123, 0, v243
	v_med3_i32 v124, v124, 0, v243
	v_med3_i32 v125, v125, 0, v243
	v_lshl_add_u32 v122, v122, 2, s10
	v_lshl_add_u32 v123, v123, 2, s10
	v_lshl_add_u32 v124, v124, 2, s10
	v_lshl_add_u32 v125, v125, 2, s10
	s_mov_b64 exec, s[78:79]
	ds_add_u32 v122, v239
	s_mov_b64 exec, s[80:81]
	ds_add_u32 v123, v239
	s_mov_b64 exec, s[82:83]
	ds_add_u32 v124, v239
	s_mov_b64 exec, s[84:85]
	ds_add_u32 v125, v239
	s_mov_b64 exec, -1
	s_cmp_le_u32 s70, 48
	s_cbranch_scc1 .Lnsel_histdone
	v_cmp_le_f32_e64 s[78:79], s72, v50
	v_cmp_le_f32_e64 s[80:81], s72, v51
	v_cmp_le_f32_e64 s[82:83], s72, v52
	v_cmp_le_f32_e64 s[84:85], s72, v53
	v_fma_f32 v50, v50, v128, v129
	v_fma_f32 v51, v51, v128, v129
	v_fma_f32 v52, v52, v128, v129
	v_fma_f32 v53, v53, v128, v129
	v_cvt_i32_f32_e32 v122, v50
	v_cvt_i32_f32_e32 v123, v51
	v_cvt_i32_f32_e32 v124, v52
	v_cvt_i32_f32_e32 v125, v53
	v_med3_i32 v122, v122, 0, v243
	v_med3_i32 v123, v123, 0, v243
	v_med3_i32 v124, v124, 0, v243
	v_med3_i32 v125, v125, 0, v243
	v_lshl_add_u32 v122, v122, 2, s10
	v_lshl_add_u32 v123, v123, 2, s10
	v_lshl_add_u32 v124, v124, 2, s10
	v_lshl_add_u32 v125, v125, 2, s10
	s_mov_b64 exec, s[78:79]
	ds_add_u32 v122, v239
	s_mov_b64 exec, s[80:81]
	ds_add_u32 v123, v239
	s_mov_b64 exec, s[82:83]
	ds_add_u32 v124, v239
	s_mov_b64 exec, s[84:85]
	ds_add_u32 v125, v239
	s_mov_b64 exec, -1
	s_cmp_le_u32 s70, 52
	s_cbranch_scc1 .Lnsel_histdone
	v_cmp_le_f32_e64 s[78:79], s72, v54
	v_cmp_le_f32_e64 s[80:81], s72, v55
	v_cmp_le_f32_e64 s[82:83], s72, v56
	v_cmp_le_f32_e64 s[84:85], s72, v57
	v_fma_f32 v54, v54, v128, v129
	v_fma_f32 v55, v55, v128, v129
	v_fma_f32 v56, v56, v128, v129
	v_fma_f32 v57, v57, v128, v129
	v_cvt_i32_f32_e32 v122, v54
	v_cvt_i32_f32_e32 v123, v55
	v_cvt_i32_f32_e32 v124, v56
	v_cvt_i32_f32_e32 v125, v57
	v_med3_i32 v122, v122, 0, v243
	v_med3_i32 v123, v123, 0, v243
	v_med3_i32 v124, v124, 0, v243
	v_med3_i32 v125, v125, 0, v243
	v_lshl_add_u32 v122, v122, 2, s10
	v_lshl_add_u32 v123, v123, 2, s10
	v_lshl_add_u32 v124, v124, 2, s10
	v_lshl_add_u32 v125, v125, 2, s10
	s_mov_b64 exec, s[78:79]
	ds_add_u32 v122, v239
	s_mov_b64 exec, s[80:81]
	ds_add_u32 v123, v239
	s_mov_b64 exec, s[82:83]
	ds_add_u32 v124, v239
	s_mov_b64 exec, s[84:85]
	ds_add_u32 v125, v239
	s_mov_b64 exec, -1
	s_cmp_le_u32 s70, 56
	s_cbranch_scc1 .Lnsel_histdone
; #define DSA_LWAIT() asm volatile("s_waitcnt lgkmcnt(0)" ::: "memory")
; __device__ __forceinline__ bool select_mask_fast(const LAS float* row, int nv, int ksel, LAS unsigned* scr, int lane, u64& word_o) {
;     ...
;     DSA_LWAIT();
;     unsigned hb[4];
; #pragma unroll
;     for (int k = 0; k < 4; ++k) hb[k] = hist[4 * lane + k];
;     const int own = (int)(hb[0] + hb[1] + hb[2] + hb[3]);
;     int suf = own;
; #pragma unroll
;     for (int o = 1; o < 64; o <<= 1) { const int t = __shfl_down(suf, o); if (lane + o < 64) suf += t; }
;     const int above = suf - own;
;     const bool mine = above < ksel && above + own >= ksel;
;     const u64 bal = __ballot(mine);
;     const int Ls = bal ? (int)__builtin_ctzll(bal) : 0;
;     int B = 0, cab = 0, nB = 0;
;     if (mine) { int acc = above; bool f = false;
; #pragma unroll
;         for (int k = 3; k >= 0; --k) { if (!f) { if (acc + (int)hb[k] >= ksel) { B = 4 * lane + k; cab = acc; nB = (int)hb[k]; f = true; } else acc += (int)hb[k]; } } }
;     { const int Lu = __builtin_amdgcn_readfirstlane(Ls); B = __builtin_amdgcn_readlane(B, Lu); cab = __builtin_amdgcn_readlane(cab, Lu); nB = __builtin_amdgcn_readlane(nB, Lu); }
;     if (nB > 64 || nB < 1) return false;
;     const int need = ksel - cab;
;     u64 myword = 0ull;
; #pragma unroll 4
;     for (int j = 0; j < R - 1; ++j) { const int key = 64 * j + lane; const float v = row[key]; int bin = (int)fmaf(v, scale, nls); bin = bin > 255 ? 255 : bin; bin = bin < 0 ? 0 : bin; const bool in = v >= lo;
;         const u64 wd = __ballot(in && bin > B); if (lane == j) myword = wd;
;         if (in && bin == B) { const unsigned slot = __hip_atomic_fetch_add(&cnt[0], 1u, __ATOMIC_RELAXED, __HIP_MEMORY_SCOPE_WORKGROUP); if (slot < 64u) { candv[slot] = v; candi[slot] = key; } } }
;     { const int j = R - 1, key = 64 * j + lane; const float v = row[key]; const bool valid = key < nv && v >= lo; int bin = (int)fmaf(v, scale, nls); bin = bin > 255 ? 255 : bin; bin = bin < 0 ? 0 : bin;
;         const u64 wd = __ballot(valid && bin > B); if (lane == j) myword = wd;
	v_cmp_le_f32_e64 s[78:79], s72, v58
	v_cmp_le_f32_e64 s[80:81], s72, v59
	v_cmp_le_f32_e64 s[82:83], s72, v60
	v_cmp_le_f32_e64 s[84:85], s72, v61
	v_fma_f32 v58, v58, v128, v129
	v_fma_f32 v59, v59, v128, v129
	v_fma_f32 v60, v60, v128, v129
	v_fma_f32 v61, v61, v128, v129
	v_cvt_i32_f32_e32 v122, v58
	v_cvt_i32_f32_e32 v123, v59
	v_cvt_i32_f32_e32 v124, v60
	v_cvt_i32_f32_e32 v125, v61
	v_med3_i32 v122, v122, 0, v243
	v_med3_i32 v123, v123, 0, v243
	v_med3_i32 v124, v124, 0, v243
	v_med3_i32 v125, v125, 0, v243
	v_lshl_add_u32 v122, v122, 2, s10
	v_lshl_add_u32 v123, v123, 2, s10
	v_lshl_add_u32 v124, v124, 2, s10
	v_lshl_add_u32 v125, v125, 2, s10
	s_mov_b64 exec, s[78:79]
	ds_add_u32 v122, v239
	s_mov_b64 exec, s[80:81]
	ds_add_u32 v123, v239
	s_mov_b64 exec, s[82:83]
	ds_add_u32 v124, v239
	s_mov_b64 exec, s[84:85]
	ds_add_u32 v125, v239
	s_mov_b64 exec, -1
	s_cmp_le_u32 s70, 60
	s_cbranch_scc1 .Lnsel_histdone
	v_cmp_le_f32_e64 s[78:79], s72, v62
	v_cmp_le_f32_e64 s[80:81], s72, v63
	v_cmp_le_f32_e64 s[82:83], s72, v64
	v_cmp_le_f32_e64 s[84:85], s72, v65
	v_fma_f32 v62, v62, v128, v129
	v_fma_f32 v63, v63, v128, v129
	v_fma_f32 v64, v64, v128, v129
	v_fma_f32 v65, v65, v128, v129
	v_cvt_i32_f32_e32 v122, v62
	v_cvt_i32_f32_e32 v123, v63
	v_cvt_i32_f32_e32 v124, v64
	v_cvt_i32_f32_e32 v125, v65
	v_med3_i32 v122, v122, 0, v243
	v_med3_i32 v123, v123, 0, v243
	v_med3_i32 v124, v124, 0, v243
	v_med3_i32 v125, v125, 0, v243
	v_lshl_add_u32 v122, v122, 2, s10
	v_lshl_add_u32 v123, v123, 2, s10
	v_lshl_add_u32 v124, v124, 2, s10
	v_lshl_add_u32 v125, v125, 2, s10
	s_mov_b64 exec, s[78:79]
	ds_add_u32 v122, v239
	s_mov_b64 exec, s[80:81]
	ds_add_u32 v123, v239
	s_mov_b64 exec, s[82:83]
	ds_add_u32 v124, v239
	s_mov_b64 exec, s[84:85]
	ds_add_u32 v125, v239
	s_mov_b64 exec, -1
.Lnsel_histdone:
	v_sub_u32_e32 v130, 63, v135
	v_lshl_add_u32 v130, v130, 4, s10
	s_waitcnt lgkmcnt(0)
	ds_read_b128 v[122:125], v130
	s_movk_i32 s76, 0x100
	s_waitcnt lgkmcnt(0)
	v_add3_u32 v131, v122, v123, v124
	v_add_u32_e32 v131, v131, v125
	v_mov_b32_e32 v132, v131
	s_nop 1
	v_add_u32_dpp v132, v132, v132 row_shr:1 row_mask:0xf bank_mask:0xf bound_ctrl:0
	s_nop 1
	v_add_u32_dpp v132, v132, v132 row_shr:2 row_mask:0xf bank_mask:0xf bound_ctrl:0
	s_nop 1
	v_add_u32_dpp v132, v132, v132 row_shr:4 row_mask:0xf bank_mask:0xf bound_ctrl:0
	s_nop 1
	v_add_u32_dpp v132, v132, v132 row_shr:8 row_mask:0xf bank_mask:0xf bound_ctrl:0
	s_nop 1
	v_add_u32_dpp v132, v132, v132 row_bcast:15 row_mask:0xa bank_mask:0xf
	s_nop 1
	v_add_u32_dpp v132, v132, v132 row_bcast:31 row_mask:0xc bank_mask:0xf
	s_nop 1
	v_sub_u32_e32 v133, v132, v131
	v_cmp_gt_u32_e64 s[78:79], s76, v133
	v_cmp_le_u32_e32 vcc, s76, v132
	s_and_b64 vcc, vcc, s[78:79]
	s_cbranch_vccz .Lnsel_bail
	s_ff1_i32_b64 s74, vcc
	s_nop 0
	v_readlane_b32 s95, v133, s74
	v_readlane_b32 s0, v125, s74
	v_readlane_b32 s1, v124, s74
	v_readlane_b32 s9, v123, s74
	v_readlane_b32 s97, v122, s74
	s_sub_i32 s75, 63, s74
	s_lshl_b32 s75, s75, 2
	s_add_i32 s77, s95, s0
	s_cmp_ge_u32 s77, s76
	s_cbranch_scc1 .Lnsel_k3
	s_mov_b32 s95, s77
	s_add_i32 s77, s95, s1
	s_cmp_ge_u32 s77, s76
	s_cbranch_scc1 .Lnsel_k2
	s_mov_b32 s95, s77
	s_add_i32 s77, s95, s9
	s_cmp_ge_u32 s77, s76
	s_cbranch_scc1 .Lnsel_k1
	s_mov_b32 s95, s77
	s_add_i32 s77, s95, s97
	s_cmp_ge_u32 s77, s76
	s_cbranch_scc0 .Lnsel_bail
	s_mov_b32 s94, s97
	s_branch .Lnsel_haveB
.Lnsel_k3:
	s_add_i32 s75, s75, 3
	s_mov_b32 s94, s0
	s_branch .Lnsel_haveB
.Lnsel_k2:
	s_add_i32 s75, s75, 2
	s_mov_b32 s94, s1
	s_branch .Lnsel_haveB
.Lnsel_k1:
	s_add_i32 s75, s75, 1
	s_mov_b32 s94, s9
.Lnsel_haveB:
	s_add_i32 s0, s94, -1
	s_cmp_gt_u32 s0, 63
	s_cbranch_scc1 .Lnsel_bail
	s_cmp_eq_u32 s75, 0
	s_cbranch_scc1 .Lnsel_bail
	s_sub_i32 s76, s76, s95
	s_mov_b32 s77, 0
	v_cvt_f32_i32_e32 v130, s75
	s_add_i32 s0, s75, 1
	v_cvt_f32_i32_e32 v131, s0
	s_cmp_eq_u32 s75, 0xff
	v_readfirstlane_b32 s74, v130
	v_readfirstlane_b32 s73, v131
	s_cselect_b32 s73, 0x7f800000, s73
	s_nop 1
	v_cmp_le_f32_e32 vcc, s73, v2
	v_cmp_le_f32_e64 s[80:81], s74, v2
	s_andn2_b64 s[80:81], s[80:81], vcc
	s_cbranch_scc1 .Lnsel_c_0
.Lnsel_nc_0:
	v_writelane_b32 v144, vcc_lo, 0
	v_writelane_b32 v145, vcc_hi, 0
	v_cmp_le_f32_e32 vcc, s73, v3
	v_cmp_le_f32_e64 s[80:81], s74, v3
	s_andn2_b64 s[80:81], s[80:81], vcc
	s_cbranch_scc1 .Lnsel_c_1
.Lnsel_nc_1:
	v_writelane_b32 v144, vcc_lo, 1
	v_writelane_b32 v145, vcc_hi, 1
	v_cmp_le_f32_e32 vcc, s73, v4
	v_cmp_le_f32_e64 s[80:81], s74, v4
	s_andn2_b64 s[80:81], s[80:81], vcc
	s_cbranch_scc1 .Lnsel_c_2
.Lnsel_nc_2:
	v_writelane_b32 v144, vcc_lo, 2
	v_writelane_b32 v145, vcc_hi, 2
	v_cmp_le_f32_e32 vcc, s73, v5
	v_cmp_le_f32_e64 s[80:81], s74, v5
	s_andn2_b64 s[80:81], s[80:81], vcc
	s_cbranch_scc1 .Lnsel_c_3
.Lnsel_nc_3:
	v_writelane_b32 v144, vcc_lo, 3
	v_writelane_b32 v145, vcc_hi, 3
	s_cmp_le_u32 s70, 4
	s_cbranch_scc1 .Lnsel_maskdone
	v_cmp_le_f32_e32 vcc, s73, v6
	v_cmp_le_f32_e64 s[80:81], s74, v6
	s_andn2_b64 s[80:81], s[80:81], vcc
	s_cbranch_scc1 .Lnsel_c_4
.Lnsel_nc_4:
	v_writelane_b32 v144, vcc_lo, 4
	v_writelane_b32 v145, vcc_hi, 4
	v_cmp_le_f32_e32 vcc, s73, v7
	v_cmp_le_f32_e64 s[80:81], s74, v7
	s_andn2_b64 s[80:81], s[80:81], vcc
	s_cbranch_scc1 .Lnsel_c_5
.Lnsel_nc_5:
	v_writelane_b32 v144, vcc_lo, 5
	v_writelane_b32 v145, vcc_hi, 5
	v_cmp_le_f32_e32 vcc, s73, v8
	v_cmp_le_f32_e64 s[80:81], s74, v8
	s_andn2_b64 s[80:81], s[80:81], vcc
	s_cbranch_scc1 .Lnsel_c_6
.Lnsel_nc_6:
	v_writelane_b32 v144, vcc_lo, 6
	v_writelane_b32 v145, vcc_hi, 6
	v_cmp_le_f32_e32 vcc, s73, v9
	v_cmp_le_f32_e64 s[80:81], s74, v9
	s_andn2_b64 s[80:81], s[80:81], vcc
	s_cbranch_scc1 .Lnsel_c_7
; __device__ __forceinline__ bool select_mask_fast(const LAS float* row, int nv, int ksel, LAS unsigned* scr, int lane, u64& word_o) {
;     ...
;     u64 myword = 0ull;
; #pragma unroll 4
;     for (int j = 0; j < R - 1; ++j) { const int key = 64 * j + lane; const float v = row[key]; int bin = (int)fmaf(v, scale, nls); bin = bin > 255 ? 255 : bin; bin = bin < 0 ? 0 : bin; const bool in = v >= lo;
;         const u64 wd = __ballot(in && bin > B); if (lane == j) myword = wd;
;         if (in && bin == B) { const unsigned slot = __hip_atomic_fetch_add(&cnt[0], 1u, __ATOMIC_RELAXED, __HIP_MEMORY_SCOPE_WORKGROUP); if (slot < 64u) { candv[slot] = v; candi[slot] = key; } } }
;     { const int j = R - 1, key = 64 * j + lane; const float v = row[key]; const bool valid = key < nv && v >= lo; int bin = (int)fmaf(v, scale, nls); bin = bin > 255 ? 255 : bin; bin = bin < 0 ? 0 : bin;
;         const u64 wd = __ballot(valid && bin > B); if (lane == j) myword = wd;
;         if (valid && bin == B) { const unsigned slot = __hip_atomic_fetch_add(&cnt[0], 1u, __ATOMIC_RELAXED, __HIP_MEMORY_SCOPE_WORKGROUP); if (slot < 64u) { candv[slot] = v; candi[slot] = key; } } }
.Lnsel_nc_7:
	v_writelane_b32 v144, vcc_lo, 7
	v_writelane_b32 v145, vcc_hi, 7
	s_cmp_le_u32 s70, 8
	s_cbranch_scc1 .Lnsel_maskdone
	v_cmp_le_f32_e32 vcc, s73, v10
	v_cmp_le_f32_e64 s[80:81], s74, v10
	s_andn2_b64 s[80:81], s[80:81], vcc
	s_cbranch_scc1 .Lnsel_c_8
.Lnsel_nc_8:
	v_writelane_b32 v144, vcc_lo, 8
	v_writelane_b32 v145, vcc_hi, 8
	v_cmp_le_f32_e32 vcc, s73, v11
	v_cmp_le_f32_e64 s[80:81], s74, v11
	s_andn2_b64 s[80:81], s[80:81], vcc
	s_cbranch_scc1 .Lnsel_c_9
.Lnsel_nc_9:
	v_writelane_b32 v144, vcc_lo, 9
	v_writelane_b32 v145, vcc_hi, 9
	v_cmp_le_f32_e32 vcc, s73, v12
	v_cmp_le_f32_e64 s[80:81], s74, v12
	s_andn2_b64 s[80:81], s[80:81], vcc
	s_cbranch_scc1 .Lnsel_c_10
.Lnsel_nc_10:
	v_writelane_b32 v144, vcc_lo, 10
	v_writelane_b32 v145, vcc_hi, 10
	v_cmp_le_f32_e32 vcc, s73, v13
	v_cmp_le_f32_e64 s[80:81], s74, v13
	s_andn2_b64 s[80:81], s[80:81], vcc
	s_cbranch_scc1 .Lnsel_c_11
.Lnsel_nc_11:
	v_writelane_b32 v144, vcc_lo, 11
	v_writelane_b32 v145, vcc_hi, 11
	s_cmp_le_u32 s70, 12
	s_cbranch_scc1 .Lnsel_maskdone
	v_cmp_le_f32_e32 vcc, s73, v14
	v_cmp_le_f32_e64 s[80:81], s74, v14
	s_andn2_b64 s[80:81], s[80:81], vcc
	s_cbranch_scc1 .Lnsel_c_12
.Lnsel_nc_12:
	v_writelane_b32 v144, vcc_lo, 12
	v_writelane_b32 v145, vcc_hi, 12
	v_cmp_le_f32_e32 vcc, s73, v15
	v_cmp_le_f32_e64 s[80:81], s74, v15
	s_andn2_b64 s[80:81], s[80:81], vcc
	s_cbranch_scc1 .Lnsel_c_13
.Lnsel_nc_13:
	v_writelane_b32 v144, vcc_lo, 13
	v_writelane_b32 v145, vcc_hi, 13
	v_cmp_le_f32_e32 vcc, s73, v16
	v_cmp_le_f32_e64 s[80:81], s74, v16
	s_andn2_b64 s[80:81], s[80:81], vcc
	s_cbranch_scc1 .Lnsel_c_14
.Lnsel_nc_14:
	v_writelane_b32 v144, vcc_lo, 14
	v_writelane_b32 v145, vcc_hi, 14
	v_cmp_le_f32_e32 vcc, s73, v17
	v_cmp_le_f32_e64 s[80:81], s74, v17
	s_andn2_b64 s[80:81], s[80:81], vcc
	s_cbranch_scc1 .Lnsel_c_15
.Lnsel_nc_15:
	v_writelane_b32 v144, vcc_lo, 15
	v_writelane_b32 v145, vcc_hi, 15
	s_cmp_le_u32 s70, 16
	s_cbranch_scc1 .Lnsel_maskdone
	v_cmp_le_f32_e32 vcc, s73, v18
	v_cmp_le_f32_e64 s[80:81], s74, v18
	s_andn2_b64 s[80:81], s[80:81], vcc
	s_cbranch_scc1 .Lnsel_c_16
.Lnsel_nc_16:
	v_writelane_b32 v144, vcc_lo, 16
	v_writelane_b32 v145, vcc_hi, 16
	v_cmp_le_f32_e32 vcc, s73, v19
	v_cmp_le_f32_e64 s[80:81], s74, v19
	s_andn2_b64 s[80:81], s[80:81], vcc
	s_cbranch_scc1 .Lnsel_c_17
.Lnsel_nc_17:
	v_writelane_b32 v144, vcc_lo, 17
	v_writelane_b32 v145, vcc_hi, 17
	v_cmp_le_f32_e32 vcc, s73, v20
	v_cmp_le_f32_e64 s[80:81], s74, v20
	s_andn2_b64 s[80:81], s[80:81], vcc
	s_cbranch_scc1 .Lnsel_c_18
.Lnsel_nc_18:
	v_writelane_b32 v144, vcc_lo, 18
	v_writelane_b32 v145, vcc_hi, 18
	v_cmp_le_f32_e32 vcc, s73, v21
	v_cmp_le_f32_e64 s[80:81], s74, v21
	s_andn2_b64 s[80:81], s[80:81], vcc
	s_cbranch_scc1 .Lnsel_c_19
.Lnsel_nc_19:
	v_writelane_b32 v144, vcc_lo, 19
	v_writelane_b32 v145, vcc_hi, 19
	s_cmp_le_u32 s70, 20
	s_cbranch_scc1 .Lnsel_maskdone
	v_cmp_le_f32_e32 vcc, s73, v22
	v_cmp_le_f32_e64 s[80:81], s74, v22
	s_andn2_b64 s[80:81], s[80:81], vcc
	s_cbranch_scc1 .Lnsel_c_20
.Lnsel_nc_20:
	v_writelane_b32 v144, vcc_lo, 20
	v_writelane_b32 v145, vcc_hi, 20
	v_cmp_le_f32_e32 vcc, s73, v23
	v_cmp_le_f32_e64 s[80:81], s74, v23
	s_andn2_b64 s[80:81], s[80:81], vcc
	s_cbranch_scc1 .Lnsel_c_21
.Lnsel_nc_21:
	v_writelane_b32 v144, vcc_lo, 21
	v_writelane_b32 v145, vcc_hi, 21
	v_cmp_le_f32_e32 vcc, s73, v24
	v_cmp_le_f32_e64 s[80:81], s74, v24
	s_andn2_b64 s[80:81], s[80:81], vcc
	s_cbranch_scc1 .Lnsel_c_22
.Lnsel_nc_22:
	v_writelane_b32 v144, vcc_lo, 22
	v_writelane_b32 v145, vcc_hi, 22
	v_cmp_le_f32_e32 vcc, s73, v25
	v_cmp_le_f32_e64 s[80:81], s74, v25
	s_andn2_b64 s[80:81], s[80:81], vcc
	s_cbranch_scc1 .Lnsel_c_23
.Lnsel_nc_23:
	v_writelane_b32 v144, vcc_lo, 23
	v_writelane_b32 v145, vcc_hi, 23
	s_cmp_le_u32 s70, 24
	s_cbranch_scc1 .Lnsel_maskdone
	v_cmp_le_f32_e32 vcc, s73, v26
	v_cmp_le_f32_e64 s[80:81], s74, v26
	s_andn2_b64 s[80:81], s[80:81], vcc
	s_cbranch_scc1 .Lnsel_c_24
.Lnsel_nc_24:
	v_writelane_b32 v144, vcc_lo, 24
	v_writelane_b32 v145, vcc_hi, 24
	v_cmp_le_f32_e32 vcc, s73, v27
	v_cmp_le_f32_e64 s[80:81], s74, v27
	s_andn2_b64 s[80:81], s[80:81], vcc
	s_cbranch_scc1 .Lnsel_c_25
.Lnsel_nc_25:
	v_writelane_b32 v144, vcc_lo, 25
	v_writelane_b32 v145, vcc_hi, 25
	v_cmp_le_f32_e32 vcc, s73, v28
	v_cmp_le_f32_e64 s[80:81], s74, v28
	s_andn2_b64 s[80:81], s[80:81], vcc
	s_cbranch_scc1 .Lnsel_c_26
.Lnsel_nc_26:
	v_writelane_b32 v144, vcc_lo, 26
	v_writelane_b32 v145, vcc_hi, 26
	v_cmp_le_f32_e32 vcc, s73, v29
	v_cmp_le_f32_e64 s[80:81], s74, v29
	s_andn2_b64 s[80:81], s[80:81], vcc
	s_cbranch_scc1 .Lnsel_c_27
.Lnsel_nc_27:
	v_writelane_b32 v144, vcc_lo, 27
	v_writelane_b32 v145, vcc_hi, 27
	s_cmp_le_u32 s70, 28
	s_cbranch_scc1 .Lnsel_maskdone
	v_cmp_le_f32_e32 vcc, s73, v30
	v_cmp_le_f32_e64 s[80:81], s74, v30
	s_andn2_b64 s[80:81], s[80:81], vcc
	s_cbranch_scc1 .Lnsel_c_28
.Lnsel_nc_28:
	v_writelane_b32 v144, vcc_lo, 28
	v_writelane_b32 v145, vcc_hi, 28
	v_cmp_le_f32_e32 vcc, s73, v31
	v_cmp_le_f32_e64 s[80:81], s74, v31
	s_andn2_b64 s[80:81], s[80:81], vcc
	s_cbranch_scc1 .Lnsel_c_29
.Lnsel_nc_29:
	v_writelane_b32 v144, vcc_lo, 29
	v_writelane_b32 v145, vcc_hi, 29
	v_cmp_le_f32_e32 vcc, s73, v32
	v_cmp_le_f32_e64 s[80:81], s74, v32
	s_andn2_b64 s[80:81], s[80:81], vcc
	s_cbranch_scc1 .Lnsel_c_30
.Lnsel_nc_30:
	v_writelane_b32 v144, vcc_lo, 30
	v_writelane_b32 v145, vcc_hi, 30
	v_cmp_le_f32_e32 vcc, s73, v33
	v_cmp_le_f32_e64 s[80:81], s74, v33
	s_andn2_b64 s[80:81], s[80:81], vcc
	s_cbranch_scc1 .Lnsel_c_31
.Lnsel_nc_31:
	v_writelane_b32 v144, vcc_lo, 31
	v_writelane_b32 v145, vcc_hi, 31
	s_cmp_le_u32 s70, 32
	s_cbranch_scc1 .Lnsel_maskdone
	v_cmp_le_f32_e32 vcc, s73, v34
	v_cmp_le_f32_e64 s[80:81], s74, v34
	s_andn2_b64 s[80:81], s[80:81], vcc
	s_cbranch_scc1 .Lnsel_c_32
; __device__ __forceinline__ bool select_mask_fast(const LAS float* row, int nv, int ksel, LAS unsigned* scr, int lane, u64& word_o) {
;     ...
;     u64 myword = 0ull;
; #pragma unroll 4
;     for (int j = 0; j < R - 1; ++j) { const int key = 64 * j + lane; const float v = row[key]; int bin = (int)fmaf(v, scale, nls); bin = bin > 255 ? 255 : bin; bin = bin < 0 ? 0 : bin; const bool in = v >= lo;
;         const u64 wd = __ballot(in && bin > B); if (lane == j) myword = wd;
;         if (in && bin == B) { const unsigned slot = __hip_atomic_fetch_add(&cnt[0], 1u, __ATOMIC_RELAXED, __HIP_MEMORY_SCOPE_WORKGROUP); if (slot < 64u) { candv[slot] = v; candi[slot] = key; } } }
;     { const int j = R - 1, key = 64 * j + lane; const float v = row[key]; const bool valid = key < nv && v >= lo; int bin = (int)fmaf(v, scale, nls); bin = bin > 255 ? 255 : bin; bin = bin < 0 ? 0 : bin;
;         const u64 wd = __ballot(valid && bin > B); if (lane == j) myword = wd;
;         if (valid && bin == B) { const unsigned slot = __hip_atomic_fetch_add(&cnt[0], 1u, __ATOMIC_RELAXED, __HIP_MEMORY_SCOPE_WORKGROUP); if (slot < 64u) { candv[slot] = v; candi[slot] = key; } } }
.Lnsel_nc_32:
	v_writelane_b32 v144, vcc_lo, 32
	v_writelane_b32 v145, vcc_hi, 32
	v_cmp_le_f32_e32 vcc, s73, v35
	v_cmp_le_f32_e64 s[80:81], s74, v35
	s_andn2_b64 s[80:81], s[80:81], vcc
	s_cbranch_scc1 .Lnsel_c_33
.Lnsel_nc_33:
	v_writelane_b32 v144, vcc_lo, 33
	v_writelane_b32 v145, vcc_hi, 33
	v_cmp_le_f32_e32 vcc, s73, v36
	v_cmp_le_f32_e64 s[80:81], s74, v36
	s_andn2_b64 s[80:81], s[80:81], vcc
	s_cbranch_scc1 .Lnsel_c_34
.Lnsel_nc_34:
	v_writelane_b32 v144, vcc_lo, 34
	v_writelane_b32 v145, vcc_hi, 34
	v_cmp_le_f32_e32 vcc, s73, v37
	v_cmp_le_f32_e64 s[80:81], s74, v37
	s_andn2_b64 s[80:81], s[80:81], vcc
	s_cbranch_scc1 .Lnsel_c_35
.Lnsel_nc_35:
	v_writelane_b32 v144, vcc_lo, 35
	v_writelane_b32 v145, vcc_hi, 35
	s_cmp_le_u32 s70, 36
	s_cbranch_scc1 .Lnsel_maskdone
	v_cmp_le_f32_e32 vcc, s73, v38
	v_cmp_le_f32_e64 s[80:81], s74, v38
	s_andn2_b64 s[80:81], s[80:81], vcc
	s_cbranch_scc1 .Lnsel_c_36
.Lnsel_nc_36:
	v_writelane_b32 v144, vcc_lo, 36
	v_writelane_b32 v145, vcc_hi, 36
	v_cmp_le_f32_e32 vcc, s73, v39
	v_cmp_le_f32_e64 s[80:81], s74, v39
	s_andn2_b64 s[80:81], s[80:81], vcc
	s_cbranch_scc1 .Lnsel_c_37
.Lnsel_nc_37:
	v_writelane_b32 v144, vcc_lo, 37
	v_writelane_b32 v145, vcc_hi, 37
	v_cmp_le_f32_e32 vcc, s73, v40
	v_cmp_le_f32_e64 s[80:81], s74, v40
	s_andn2_b64 s[80:81], s[80:81], vcc
	s_cbranch_scc1 .Lnsel_c_38
.Lnsel_nc_38:
	v_writelane_b32 v144, vcc_lo, 38
	v_writelane_b32 v145, vcc_hi, 38
	v_cmp_le_f32_e32 vcc, s73, v41
	v_cmp_le_f32_e64 s[80:81], s74, v41
	s_andn2_b64 s[80:81], s[80:81], vcc
	s_cbranch_scc1 .Lnsel_c_39
.Lnsel_nc_39:
	v_writelane_b32 v144, vcc_lo, 39
	v_writelane_b32 v145, vcc_hi, 39
	s_cmp_le_u32 s70, 40
	s_cbranch_scc1 .Lnsel_maskdone
	v_cmp_le_f32_e32 vcc, s73, v42
	v_cmp_le_f32_e64 s[80:81], s74, v42
	s_andn2_b64 s[80:81], s[80:81], vcc
	s_cbranch_scc1 .Lnsel_c_40
.Lnsel_nc_40:
	v_writelane_b32 v144, vcc_lo, 40
	v_writelane_b32 v145, vcc_hi, 40
	v_cmp_le_f32_e32 vcc, s73, v43
	v_cmp_le_f32_e64 s[80:81], s74, v43
	s_andn2_b64 s[80:81], s[80:81], vcc
	s_cbranch_scc1 .Lnsel_c_41
.Lnsel_nc_41:
	v_writelane_b32 v144, vcc_lo, 41
	v_writelane_b32 v145, vcc_hi, 41
	v_cmp_le_f32_e32 vcc, s73, v44
	v_cmp_le_f32_e64 s[80:81], s74, v44
	s_andn2_b64 s[80:81], s[80:81], vcc
	s_cbranch_scc1 .Lnsel_c_42
.Lnsel_nc_42:
	v_writelane_b32 v144, vcc_lo, 42
	v_writelane_b32 v145, vcc_hi, 42
	v_cmp_le_f32_e32 vcc, s73, v45
	v_cmp_le_f32_e64 s[80:81], s74, v45
	s_andn2_b64 s[80:81], s[80:81], vcc
	s_cbranch_scc1 .Lnsel_c_43
.Lnsel_nc_43:
	v_writelane_b32 v144, vcc_lo, 43
	v_writelane_b32 v145, vcc_hi, 43
	s_cmp_le_u32 s70, 44
	s_cbranch_scc1 .Lnsel_maskdone
	v_cmp_le_f32_e32 vcc, s73, v46
	v_cmp_le_f32_e64 s[80:81], s74, v46
	s_andn2_b64 s[80:81], s[80:81], vcc
	s_cbranch_scc1 .Lnsel_c_44
.Lnsel_nc_44:
	v_writelane_b32 v144, vcc_lo, 44
	v_writelane_b32 v145, vcc_hi, 44
	v_cmp_le_f32_e32 vcc, s73, v47
	v_cmp_le_f32_e64 s[80:81], s74, v47
	s_andn2_b64 s[80:81], s[80:81], vcc
	s_cbranch_scc1 .Lnsel_c_45
.Lnsel_nc_45:
	v_writelane_b32 v144, vcc_lo, 45
	v_writelane_b32 v145, vcc_hi, 45
	v_cmp_le_f32_e32 vcc, s73, v48
	v_cmp_le_f32_e64 s[80:81], s74, v48
	s_andn2_b64 s[80:81], s[80:81], vcc
	s_cbranch_scc1 .Lnsel_c_46
.Lnsel_nc_46:
	v_writelane_b32 v144, vcc_lo, 46
	v_writelane_b32 v145, vcc_hi, 46
	v_cmp_le_f32_e32 vcc, s73, v49
	v_cmp_le_f32_e64 s[80:81], s74, v49
	s_andn2_b64 s[80:81], s[80:81], vcc
	s_cbranch_scc1 .Lnsel_c_47
.Lnsel_nc_47:
	v_writelane_b32 v144, vcc_lo, 47
	v_writelane_b32 v145, vcc_hi, 47
	s_cmp_le_u32 s70, 48
	s_cbranch_scc1 .Lnsel_maskdone
	v_cmp_le_f32_e32 vcc, s73, v50
	v_cmp_le_f32_e64 s[80:81], s74, v50
	s_andn2_b64 s[80:81], s[80:81], vcc
	s_cbranch_scc1 .Lnsel_c_48
.Lnsel_nc_48:
	v_writelane_b32 v144, vcc_lo, 48
	v_writelane_b32 v145, vcc_hi, 48
	v_cmp_le_f32_e32 vcc, s73, v51
	v_cmp_le_f32_e64 s[80:81], s74, v51
	s_andn2_b64 s[80:81], s[80:81], vcc
	s_cbranch_scc1 .Lnsel_c_49
.Lnsel_nc_49:
	v_writelane_b32 v144, vcc_lo, 49
	v_writelane_b32 v145, vcc_hi, 49
	v_cmp_le_f32_e32 vcc, s73, v52
	v_cmp_le_f32_e64 s[80:81], s74, v52
	s_andn2_b64 s[80:81], s[80:81], vcc
	s_cbranch_scc1 .Lnsel_c_50
.Lnsel_nc_50:
	v_writelane_b32 v144, vcc_lo, 50
	v_writelane_b32 v145, vcc_hi, 50
	v_cmp_le_f32_e32 vcc, s73, v53
	v_cmp_le_f32_e64 s[80:81], s74, v53
	s_andn2_b64 s[80:81], s[80:81], vcc
	s_cbranch_scc1 .Lnsel_c_51
; #define DSA_LWAIT() asm volatile("s_waitcnt lgkmcnt(0)" ::: "memory")
; __device__ __forceinline__ bool select_mask_fast(const LAS float* row, int nv, int ksel, LAS unsigned* scr, int lane, u64& word_o) {
;     ...
;     DSA_LWAIT();
;     const float mv = lane < nB ? candv[lane] : -INFINITY; const int mi = lane < nB ? candi[lane] : 0x7fffffff; int rank = 0;
;     { const int nBu = __builtin_amdgcn_readfirstlane(nB);
;       for (int m = 0; m < nBu; ++m) { const float ov = __builtin_bit_cast(float, __builtin_amdgcn_readlane(__builtin_bit_cast(int, mv), m)); const int oi = __builtin_amdgcn_readlane(mi, m);
;           rank += (ov > mv || (ov == mv && oi < mi)) ? 1 : 0; } }
;     u64 sb = __ballot(lane < nB && rank < need);
;     while (sb) { const int c = (int)__builtin_ctzll(sb); sb &= sb - 1ull; const int km = __builtin_amdgcn_readlane(mi, c); if (lane == (km >> 6)) myword |= 1ull << (km & 63); }
;     word_o = myword; return true;
.Lnsel_nc_51:
	v_writelane_b32 v144, vcc_lo, 51
	v_writelane_b32 v145, vcc_hi, 51
	s_cmp_le_u32 s70, 52
	s_cbranch_scc1 .Lnsel_maskdone
	v_cmp_le_f32_e32 vcc, s73, v54
	v_cmp_le_f32_e64 s[80:81], s74, v54
	s_andn2_b64 s[80:81], s[80:81], vcc
	s_cbranch_scc1 .Lnsel_c_52
.Lnsel_nc_52:
	v_writelane_b32 v144, vcc_lo, 52
	v_writelane_b32 v145, vcc_hi, 52
	v_cmp_le_f32_e32 vcc, s73, v55
	v_cmp_le_f32_e64 s[80:81], s74, v55
	s_andn2_b64 s[80:81], s[80:81], vcc
	s_cbranch_scc1 .Lnsel_c_53
.Lnsel_nc_53:
	v_writelane_b32 v144, vcc_lo, 53
	v_writelane_b32 v145, vcc_hi, 53
	v_cmp_le_f32_e32 vcc, s73, v56
	v_cmp_le_f32_e64 s[80:81], s74, v56
	s_andn2_b64 s[80:81], s[80:81], vcc
	s_cbranch_scc1 .Lnsel_c_54
.Lnsel_nc_54:
	v_writelane_b32 v144, vcc_lo, 54
	v_writelane_b32 v145, vcc_hi, 54
	v_cmp_le_f32_e32 vcc, s73, v57
	v_cmp_le_f32_e64 s[80:81], s74, v57
	s_andn2_b64 s[80:81], s[80:81], vcc
	s_cbranch_scc1 .Lnsel_c_55
.Lnsel_nc_55:
	v_writelane_b32 v144, vcc_lo, 55
	v_writelane_b32 v145, vcc_hi, 55
	s_cmp_le_u32 s70, 56
	s_cbranch_scc1 .Lnsel_maskdone
	v_cmp_le_f32_e32 vcc, s73, v58
	v_cmp_le_f32_e64 s[80:81], s74, v58
	s_andn2_b64 s[80:81], s[80:81], vcc
	s_cbranch_scc1 .Lnsel_c_56
.Lnsel_nc_56:
	v_writelane_b32 v144, vcc_lo, 56
	v_writelane_b32 v145, vcc_hi, 56
	v_cmp_le_f32_e32 vcc, s73, v59
	v_cmp_le_f32_e64 s[80:81], s74, v59
	s_andn2_b64 s[80:81], s[80:81], vcc
	s_cbranch_scc1 .Lnsel_c_57
.Lnsel_nc_57:
	v_writelane_b32 v144, vcc_lo, 57
	v_writelane_b32 v145, vcc_hi, 57
	v_cmp_le_f32_e32 vcc, s73, v60
	v_cmp_le_f32_e64 s[80:81], s74, v60
	s_andn2_b64 s[80:81], s[80:81], vcc
	s_cbranch_scc1 .Lnsel_c_58
.Lnsel_nc_58:
	v_writelane_b32 v144, vcc_lo, 58
	v_writelane_b32 v145, vcc_hi, 58
	v_cmp_le_f32_e32 vcc, s73, v61
	v_cmp_le_f32_e64 s[80:81], s74, v61
	s_andn2_b64 s[80:81], s[80:81], vcc
	s_cbranch_scc1 .Lnsel_c_59
.Lnsel_nc_59:
	v_writelane_b32 v144, vcc_lo, 59
	v_writelane_b32 v145, vcc_hi, 59
	s_cmp_le_u32 s70, 60
	s_cbranch_scc1 .Lnsel_maskdone
	v_cmp_le_f32_e32 vcc, s73, v62
	v_cmp_le_f32_e64 s[80:81], s74, v62
	s_andn2_b64 s[80:81], s[80:81], vcc
	s_cbranch_scc1 .Lnsel_c_60
.Lnsel_nc_60:
	v_writelane_b32 v144, vcc_lo, 60
	v_writelane_b32 v145, vcc_hi, 60
	v_cmp_le_f32_e32 vcc, s73, v63
	v_cmp_le_f32_e64 s[80:81], s74, v63
	s_andn2_b64 s[80:81], s[80:81], vcc
	s_cbranch_scc1 .Lnsel_c_61
.Lnsel_nc_61:
	v_writelane_b32 v144, vcc_lo, 61
	v_writelane_b32 v145, vcc_hi, 61
	v_cmp_le_f32_e32 vcc, s73, v64
	v_cmp_le_f32_e64 s[80:81], s74, v64
	s_andn2_b64 s[80:81], s[80:81], vcc
	s_cbranch_scc1 .Lnsel_c_62
.Lnsel_nc_62:
	v_writelane_b32 v144, vcc_lo, 62
	v_writelane_b32 v145, vcc_hi, 62
	v_cmp_le_f32_e32 vcc, s73, v65
	v_cmp_le_f32_e64 s[80:81], s74, v65
	s_andn2_b64 s[80:81], s[80:81], vcc
	s_cbranch_scc1 .Lnsel_c_63
.Lnsel_nc_63:
	v_writelane_b32 v144, vcc_lo, 63
	v_writelane_b32 v145, vcc_hi, 63
.Lnsel_maskdone:
	v_lshl_add_u32 v130, v135, 2, s10
	s_waitcnt lgkmcnt(0)
	ds_read_b32 v122, v130 offset:1024
	ds_read_b32 v123, v130 offset:1280
	v_cmp_gt_u32_e64 s[78:79], s94, v135
	v_bfrev_b32_e32 v131, -2
	v_mov_b32_e32 v124, 0
	s_mov_b32 s97, 0
	s_waitcnt lgkmcnt(0)
	v_cndmask_b32_e64 v122, v127, v122, s[78:79]
	v_cndmask_b32_e64 v123, v131, v123, s[78:79]
	s_nop 0
.Lnsel_rank:
	v_readlane_b32 s0, v122, s97
	v_readlane_b32 s1, v123, s97
	s_add_i32 s97, s97, 1
	s_nop 0
	v_cmp_gt_f32_e64 s[80:81], s0, v122
	v_cmp_eq_f32_e64 s[82:83], s0, v122
	v_cmp_lt_i32_e64 s[84:85], s1, v123
	s_and_b64 s[82:83], s[82:83], s[84:85]
	s_or_b64 s[80:81], s[80:81], s[82:83]
	s_cmp_eq_u32 s94, s97
	v_addc_co_u32_e64 v124, s[80:81], 0, v124, s[80:81]
	s_cbranch_scc0 .Lnsel_rank
	v_cmp_gt_i32_e32 vcc, s76, v124
	s_and_b64 vcc, vcc, s[78:79]
	s_cbranch_vccz .Lnsel_done
.Lnsel_or:
	s_ff1_i32_b64 s9, vcc
	s_add_u32 s0, vcc_lo, -1
	s_addc_u32 s1, vcc_hi, -1
	v_readlane_b32 s9, v123, s9
	s_and_b64 vcc, s[0:1], vcc
	s_ashr_i32 s95, s9, 6
	s_lshl_b64 s[0:1], 1, s9
	v_mov_b32_e32 v130, s1
	v_mov_b32_e32 v131, s0
	v_cmp_eq_u32_e64 s[0:1], s95, v135
	s_cmp_lg_u64 vcc, 0
	s_nop 0
	v_cndmask_b32_e64 v130, 0, v130, s[0:1]
	v_cndmask_b32_e64 v131, 0, v131, s[0:1]
	v_or_b32_e32 v145, v130, v145
	v_or_b32_e32 v144, v131, v144
	s_cbranch_scc1 .Lnsel_or

; #define SMF_FOR(...) { _Pragma("unroll 4") for (int j = 0; j < R - 1; ++j) { const int key = 64 * j + lane; const float v = row[key]; (void)key; __VA_ARGS__ } \
;                        { const int key = 64 * (R - 1) + lane; if (key < nv) { const float v = row[key]; __VA_ARGS__ } } }
; __device__ __forceinline__ bool select_mask_fast(const LAS float* row, int nv, int ksel, LAS unsigned* scr, int lane, u64& word_o) {
;     ...
;     float m0 = -INFINITY, m1 = -INFINITY, m2 = -INFINITY, m3 = -INFINITY;
;     SMF_FOR({ const float n1 = __builtin_amdgcn_fmed3f(m0, m1, v), n2 = __builtin_amdgcn_fmed3f(m1, m2, v), n3 = __builtin_amdgcn_fmed3f(m2, m3, v); m0 = __builtin_amdgcn_fmed3f(m0, v, BIGF); m1 = n1; m2 = n2; m3 = n3; })
.Lnsel_fix_0:
	v_cmp_le_i32_e64 s[78:79], 0, v126
	v_cmp_le_i32_e64 s[80:81], 1, v126
	v_cmp_le_i32_e64 s[82:83], 2, v126
	v_cmp_le_i32_e64 s[84:85], 3, v126
	v_cndmask_b32_e64 v2, v127, v2, s[78:79]
	v_cndmask_b32_e64 v3, v127, v3, s[80:81]
	v_cndmask_b32_e64 v4, v127, v4, s[82:83]
	v_cndmask_b32_e64 v5, v127, v5, s[84:85]
	s_branch .Lnsel_fixed_0
.Lnsel_fix_1:
	v_cmp_le_i32_e64 s[78:79], 4, v126
	v_cmp_le_i32_e64 s[80:81], 5, v126
	v_cmp_le_i32_e64 s[82:83], 6, v126
	v_cmp_le_i32_e64 s[84:85], 7, v126
	v_cndmask_b32_e64 v6, v127, v6, s[78:79]
	v_cndmask_b32_e64 v7, v127, v7, s[80:81]
	v_cndmask_b32_e64 v8, v127, v8, s[82:83]
	v_cndmask_b32_e64 v9, v127, v9, s[84:85]
	s_branch .Lnsel_fixed_1
.Lnsel_fix_2:
	v_cmp_le_i32_e64 s[78:79], 8, v126
	v_cmp_le_i32_e64 s[80:81], 9, v126
	v_cmp_le_i32_e64 s[82:83], 10, v126
	v_cmp_le_i32_e64 s[84:85], 11, v126
	v_cndmask_b32_e64 v10, v127, v10, s[78:79]
	v_cndmask_b32_e64 v11, v127, v11, s[80:81]
	v_cndmask_b32_e64 v12, v127, v12, s[82:83]
	v_cndmask_b32_e64 v13, v127, v13, s[84:85]
	s_branch .Lnsel_fixed_2
.Lnsel_fix_3:
	v_cmp_le_i32_e64 s[78:79], 12, v126
	v_cmp_le_i32_e64 s[80:81], 13, v126
	v_cmp_le_i32_e64 s[82:83], 14, v126
	v_cmp_le_i32_e64 s[84:85], 15, v126
	v_cndmask_b32_e64 v14, v127, v14, s[78:79]
	v_cndmask_b32_e64 v15, v127, v15, s[80:81]
	v_cndmask_b32_e64 v16, v127, v16, s[82:83]
	v_cndmask_b32_e64 v17, v127, v17, s[84:85]
	s_branch .Lnsel_fixed_3
.Lnsel_fix_4:
	v_cmp_le_i32_e64 s[78:79], 16, v126
	v_cmp_le_i32_e64 s[80:81], 17, v126
	v_cmp_le_i32_e64 s[82:83], 18, v126
	v_cmp_le_i32_e64 s[84:85], 19, v126
	v_cndmask_b32_e64 v18, v127, v18, s[78:79]
	v_cndmask_b32_e64 v19, v127, v19, s[80:81]
	v_cndmask_b32_e64 v20, v127, v20, s[82:83]
	v_cndmask_b32_e64 v21, v127, v21, s[84:85]
	s_branch .Lnsel_fixed_4
.Lnsel_fix_5:
	v_cmp_le_i32_e64 s[78:79], 20, v126
	v_cmp_le_i32_e64 s[80:81], 21, v126
	v_cmp_le_i32_e64 s[82:83], 22, v126
	v_cmp_le_i32_e64 s[84:85], 23, v126
	v_cndmask_b32_e64 v22, v127, v22, s[78:79]
	v_cndmask_b32_e64 v23, v127, v23, s[80:81]
	v_cndmask_b32_e64 v24, v127, v24, s[82:83]
	v_cndmask_b32_e64 v25, v127, v25, s[84:85]
	s_branch .Lnsel_fixed_5
.Lnsel_fix_6:
	v_cmp_le_i32_e64 s[78:79], 24, v126
	v_cmp_le_i32_e64 s[80:81], 25, v126
	v_cmp_le_i32_e64 s[82:83], 26, v126
	v_cmp_le_i32_e64 s[84:85], 27, v126
	v_cndmask_b32_e64 v26, v127, v26, s[78:79]
	v_cndmask_b32_e64 v27, v127, v27, s[80:81]
	v_cndmask_b32_e64 v28, v127, v28, s[82:83]
	v_cndmask_b32_e64 v29, v127, v29, s[84:85]
	s_branch .Lnsel_fixed_6
.Lnsel_fix_7:
	v_cmp_le_i32_e64 s[78:79], 28, v126
	v_cmp_le_i32_e64 s[80:81], 29, v126
	v_cmp_le_i32_e64 s[82:83], 30, v126
	v_cmp_le_i32_e64 s[84:85], 31, v126
	v_cndmask_b32_e64 v30, v127, v30, s[78:79]
	v_cndmask_b32_e64 v31, v127, v31, s[80:81]
	v_cndmask_b32_e64 v32, v127, v32, s[82:83]
	v_cndmask_b32_e64 v33, v127, v33, s[84:85]
	s_branch .Lnsel_fixed_7
.Lnsel_fix_8:
	v_cmp_le_i32_e64 s[78:79], 32, v126
	v_cmp_le_i32_e64 s[80:81], 33, v126
	v_cmp_le_i32_e64 s[82:83], 34, v126
	v_cmp_le_i32_e64 s[84:85], 35, v126
	v_cndmask_b32_e64 v34, v127, v34, s[78:79]
	v_cndmask_b32_e64 v35, v127, v35, s[80:81]
	v_cndmask_b32_e64 v36, v127, v36, s[82:83]
	v_cndmask_b32_e64 v37, v127, v37, s[84:85]
	s_branch .Lnsel_fixed_8
.Lnsel_fix_9:
	v_cmp_le_i32_e64 s[78:79], 36, v126
	v_cmp_le_i32_e64 s[80:81], 37, v126
	v_cmp_le_i32_e64 s[82:83], 38, v126
	v_cmp_le_i32_e64 s[84:85], 39, v126
	v_cndmask_b32_e64 v38, v127, v38, s[78:79]
	v_cndmask_b32_e64 v39, v127, v39, s[80:81]
	v_cndmask_b32_e64 v40, v127, v40, s[82:83]
	v_cndmask_b32_e64 v41, v127, v41, s[84:85]
	s_branch .Lnsel_fixed_9
.Lnsel_fix_10:
	v_cmp_le_i32_e64 s[78:79], 40, v126
	v_cmp_le_i32_e64 s[80:81], 41, v126
	v_cmp_le_i32_e64 s[82:83], 42, v126
	v_cmp_le_i32_e64 s[84:85], 43, v126
	v_cndmask_b32_e64 v42, v127, v42, s[78:79]
	v_cndmask_b32_e64 v43, v127, v43, s[80:81]
	v_cndmask_b32_e64 v44, v127, v44, s[82:83]
	v_cndmask_b32_e64 v45, v127, v45, s[84:85]
	s_branch .Lnsel_fixed_10
.Lnsel_fix_11:
	v_cmp_le_i32_e64 s[78:79], 44, v126
	v_cmp_le_i32_e64 s[80:81], 45, v126
	v_cmp_le_i32_e64 s[82:83], 46, v126
	v_cmp_le_i32_e64 s[84:85], 47, v126
	v_cndmask_b32_e64 v46, v127, v46, s[78:79]
	v_cndmask_b32_e64 v47, v127, v47, s[80:81]
	v_cndmask_b32_e64 v48, v127, v48, s[82:83]
	v_cndmask_b32_e64 v49, v127, v49, s[84:85]
	s_branch .Lnsel_fixed_11
.Lnsel_fix_12:
	v_cmp_le_i32_e64 s[78:79], 48, v126
	v_cmp_le_i32_e64 s[80:81], 49, v126
	v_cmp_le_i32_e64 s[82:83], 50, v126
	v_cmp_le_i32_e64 s[84:85], 51, v126
	v_cndmask_b32_e64 v50, v127, v50, s[78:79]
	v_cndmask_b32_e64 v51, v127, v51, s[80:81]
	v_cndmask_b32_e64 v52, v127, v52, s[82:83]
	v_cndmask_b32_e64 v53, v127, v53, s[84:85]
	s_branch .Lnsel_fixed_12
.Lnsel_fix_13:
	v_cmp_le_i32_e64 s[78:79], 52, v126
	v_cmp_le_i32_e64 s[80:81], 53, v126
	v_cmp_le_i32_e64 s[82:83], 54, v126
	v_cmp_le_i32_e64 s[84:85], 55, v126
	v_cndmask_b32_e64 v54, v127, v54, s[78:79]
	v_cndmask_b32_e64 v55, v127, v55, s[80:81]
	v_cndmask_b32_e64 v56, v127, v56, s[82:83]
	v_cndmask_b32_e64 v57, v127, v57, s[84:85]
	s_branch .Lnsel_fixed_13
.Lnsel_fix_14:
	v_cmp_le_i32_e64 s[78:79], 56, v126
	v_cmp_le_i32_e64 s[80:81], 57, v126
	v_cmp_le_i32_e64 s[82:83], 58, v126
	v_cmp_le_i32_e64 s[84:85], 59, v126
	v_cndmask_b32_e64 v58, v127, v58, s[78:79]
	v_cndmask_b32_e64 v59, v127, v59, s[80:81]
	v_cndmask_b32_e64 v60, v127, v60, s[82:83]
	v_cndmask_b32_e64 v61, v127, v61, s[84:85]
	s_branch .Lnsel_fixed_14
.Lnsel_fix_15:
	v_cmp_le_i32_e64 s[78:79], 60, v126
	v_cmp_le_i32_e64 s[80:81], 61, v126
	v_cmp_le_i32_e64 s[82:83], 62, v126
	v_cmp_le_i32_e64 s[84:85], 63, v126
	v_cndmask_b32_e64 v62, v127, v62, s[78:79]
	v_cndmask_b32_e64 v63, v127, v63, s[80:81]
	v_cndmask_b32_e64 v64, v127, v64, s[82:83]
	v_cndmask_b32_e64 v65, v127, v65, s[84:85]
	s_branch .Lnsel_fixed_15
; __device__ __forceinline__ bool select_mask_fast(const LAS float* row, int nv, int ksel, LAS unsigned* scr, int lane, u64& word_o) {
;     ...
;     for (int j = 0; j < R - 1; ++j) { const int key = 64 * j + lane; const float v = row[key]; int bin = (int)fmaf(v, scale, nls); bin = bin > 255 ? 255 : bin; bin = bin < 0 ? 0 : bin; const bool in = v >= lo;
;         const u64 wd = __ballot(in && bin > B); if (lane == j) myword = wd;
;         if (in && bin == B) { const unsigned slot = __hip_atomic_fetch_add(&cnt[0], 1u, __ATOMIC_RELAXED, __HIP_MEMORY_SCOPE_WORKGROUP); if (slot < 64u) { candv[slot] = v; candi[slot] = key; } } }
;     { const int j = R - 1, key = 64 * j + lane; const float v = row[key]; const bool valid = key < nv && v >= lo; int bin = (int)fmaf(v, scale, nls); bin = bin > 255 ? 255 : bin; bin = bin < 0 ? 0 : bin;
;         const u64 wd = __ballot(valid && bin > B); if (lane == j) myword = wd;
;         if (valid && bin == B) { const unsigned slot = __hip_atomic_fetch_add(&cnt[0], 1u, __ATOMIC_RELAXED, __HIP_MEMORY_SCOPE_WORKGROUP); if (slot < 64u) { candv[slot] = v; candi[slot] = key; } } }
.Lnsel_c_0:
	s_mov_b64 exec, s[80:81]
	ds_read_b32 v132, v146 offset:0
	v_mbcnt_lo_u32_b32 v130, s80, 0
	v_mbcnt_hi_u32_b32 v130, s81, v130
	v_add_u32_e32 v130, s77, v130
	v_lshl_add_u32 v130, v130, 2, s10
	v_add_u32_e32 v131, 0, v135
	s_waitcnt lgkmcnt(0)
	ds_write2st64_b32 v130, v132, v131 offset0:4 offset1:5
	s_bcnt1_i32_b64 s0, s[80:81]
	s_add_i32 s77, s77, s0
	s_mov_b64 exec, -1
	s_branch .Lnsel_nc_0
.Lnsel_c_1:
	s_mov_b64 exec, s[80:81]
	ds_read_b32 v132, v146 offset:256
	v_mbcnt_lo_u32_b32 v130, s80, 0
	v_mbcnt_hi_u32_b32 v130, s81, v130
	v_add_u32_e32 v130, s77, v130
	v_lshl_add_u32 v130, v130, 2, s10
	v_add_u32_e32 v131, 64, v135
	s_waitcnt lgkmcnt(0)
	ds_write2st64_b32 v130, v132, v131 offset0:4 offset1:5
	s_bcnt1_i32_b64 s0, s[80:81]
	s_add_i32 s77, s77, s0
	s_mov_b64 exec, -1
	s_branch .Lnsel_nc_1
.Lnsel_c_2:
	s_mov_b64 exec, s[80:81]
	ds_read_b32 v132, v146 offset:512
	v_mbcnt_lo_u32_b32 v130, s80, 0
	v_mbcnt_hi_u32_b32 v130, s81, v130
	v_add_u32_e32 v130, s77, v130
	v_lshl_add_u32 v130, v130, 2, s10
	v_add_u32_e32 v131, 0x80, v135
	s_waitcnt lgkmcnt(0)
	ds_write2st64_b32 v130, v132, v131 offset0:4 offset1:5
	s_bcnt1_i32_b64 s0, s[80:81]
	s_add_i32 s77, s77, s0
	s_mov_b64 exec, -1
	s_branch .Lnsel_nc_2
.Lnsel_c_3:
	s_mov_b64 exec, s[80:81]
	ds_read_b32 v132, v146 offset:768
	v_mbcnt_lo_u32_b32 v130, s80, 0
	v_mbcnt_hi_u32_b32 v130, s81, v130
	v_add_u32_e32 v130, s77, v130
	v_lshl_add_u32 v130, v130, 2, s10
	v_add_u32_e32 v131, 0xc0, v135
	s_waitcnt lgkmcnt(0)
	ds_write2st64_b32 v130, v132, v131 offset0:4 offset1:5
	s_bcnt1_i32_b64 s0, s[80:81]
	s_add_i32 s77, s77, s0
	s_mov_b64 exec, -1
	s_branch .Lnsel_nc_3
.Lnsel_c_4:
	s_mov_b64 exec, s[80:81]
	ds_read_b32 v132, v146 offset:1024
	v_mbcnt_lo_u32_b32 v130, s80, 0
	v_mbcnt_hi_u32_b32 v130, s81, v130
	v_add_u32_e32 v130, s77, v130
	v_lshl_add_u32 v130, v130, 2, s10
	v_add_u32_e32 v131, 0x100, v135
	s_waitcnt lgkmcnt(0)
	ds_write2st64_b32 v130, v132, v131 offset0:4 offset1:5
	s_bcnt1_i32_b64 s0, s[80:81]
	s_add_i32 s77, s77, s0
	s_mov_b64 exec, -1
	s_branch .Lnsel_nc_4
.Lnsel_c_5:
	s_mov_b64 exec, s[80:81]
	ds_read_b32 v132, v146 offset:1280
	v_mbcnt_lo_u32_b32 v130, s80, 0
	v_mbcnt_hi_u32_b32 v130, s81, v130
	v_add_u32_e32 v130, s77, v130
	v_lshl_add_u32 v130, v130, 2, s10
	v_add_u32_e32 v131, 0x140, v135
	s_waitcnt lgkmcnt(0)
	ds_write2st64_b32 v130, v132, v131 offset0:4 offset1:5
	s_bcnt1_i32_b64 s0, s[80:81]
	s_add_i32 s77, s77, s0
	s_mov_b64 exec, -1
	s_branch .Lnsel_nc_5
.Lnsel_c_6:
	s_mov_b64 exec, s[80:81]
	ds_read_b32 v132, v146 offset:1536
	v_mbcnt_lo_u32_b32 v130, s80, 0
	v_mbcnt_hi_u32_b32 v130, s81, v130
	v_add_u32_e32 v130, s77, v130
	v_lshl_add_u32 v130, v130, 2, s10
	v_add_u32_e32 v131, 0x180, v135
	s_waitcnt lgkmcnt(0)
	ds_write2st64_b32 v130, v132, v131 offset0:4 offset1:5
	s_bcnt1_i32_b64 s0, s[80:81]
	s_add_i32 s77, s77, s0
	s_mov_b64 exec, -1
	s_branch .Lnsel_nc_6
.Lnsel_c_7:
	s_mov_b64 exec, s[80:81]
	ds_read_b32 v132, v146 offset:1792
	v_mbcnt_lo_u32_b32 v130, s80, 0
	v_mbcnt_hi_u32_b32 v130, s81, v130
	v_add_u32_e32 v130, s77, v130
	v_lshl_add_u32 v130, v130, 2, s10
	v_add_u32_e32 v131, 0x1c0, v135
	s_waitcnt lgkmcnt(0)
	ds_write2st64_b32 v130, v132, v131 offset0:4 offset1:5
	s_bcnt1_i32_b64 s0, s[80:81]
	s_add_i32 s77, s77, s0
	s_mov_b64 exec, -1
	s_branch .Lnsel_nc_7
.Lnsel_c_8:
	s_mov_b64 exec, s[80:81]
	ds_read_b32 v132, v146 offset:2048
	v_mbcnt_lo_u32_b32 v130, s80, 0
	v_mbcnt_hi_u32_b32 v130, s81, v130
	v_add_u32_e32 v130, s77, v130
	v_lshl_add_u32 v130, v130, 2, s10
	v_add_u32_e32 v131, 0x200, v135
	s_waitcnt lgkmcnt(0)
	ds_write2st64_b32 v130, v132, v131 offset0:4 offset1:5
	s_bcnt1_i32_b64 s0, s[80:81]
	s_add_i32 s77, s77, s0
	s_mov_b64 exec, -1
	s_branch .Lnsel_nc_8
.Lnsel_c_9:
	s_mov_b64 exec, s[80:81]
	ds_read_b32 v132, v146 offset:2304
	v_mbcnt_lo_u32_b32 v130, s80, 0
	v_mbcnt_hi_u32_b32 v130, s81, v130
	v_add_u32_e32 v130, s77, v130
	v_lshl_add_u32 v130, v130, 2, s10
	v_add_u32_e32 v131, 0x240, v135
	s_waitcnt lgkmcnt(0)
	ds_write2st64_b32 v130, v132, v131 offset0:4 offset1:5
	s_bcnt1_i32_b64 s0, s[80:81]
	s_add_i32 s77, s77, s0
	s_mov_b64 exec, -1
	s_branch .Lnsel_nc_9
.Lnsel_c_10:
	s_mov_b64 exec, s[80:81]
	ds_read_b32 v132, v146 offset:2560
	v_mbcnt_lo_u32_b32 v130, s80, 0
	v_mbcnt_hi_u32_b32 v130, s81, v130
	v_add_u32_e32 v130, s77, v130
	v_lshl_add_u32 v130, v130, 2, s10
	v_add_u32_e32 v131, 0x280, v135
	s_waitcnt lgkmcnt(0)
	ds_write2st64_b32 v130, v132, v131 offset0:4 offset1:5
	s_bcnt1_i32_b64 s0, s[80:81]
	s_add_i32 s77, s77, s0
	s_mov_b64 exec, -1
	s_branch .Lnsel_nc_10
.Lnsel_c_11:
	s_mov_b64 exec, s[80:81]
	ds_read_b32 v132, v146 offset:2816
	v_mbcnt_lo_u32_b32 v130, s80, 0
	v_mbcnt_hi_u32_b32 v130, s81, v130
	v_add_u32_e32 v130, s77, v130
	v_lshl_add_u32 v130, v130, 2, s10
	v_add_u32_e32 v131, 0x2c0, v135
	s_waitcnt lgkmcnt(0)
	ds_write2st64_b32 v130, v132, v131 offset0:4 offset1:5
	s_bcnt1_i32_b64 s0, s[80:81]
	s_add_i32 s77, s77, s0
	s_mov_b64 exec, -1
	s_branch .Lnsel_nc_11
.Lnsel_c_12:
	s_mov_b64 exec, s[80:81]
	ds_read_b32 v132, v146 offset:3072
	v_mbcnt_lo_u32_b32 v130, s80, 0
	v_mbcnt_hi_u32_b32 v130, s81, v130
	v_add_u32_e32 v130, s77, v130
	v_lshl_add_u32 v130, v130, 2, s10
	v_add_u32_e32 v131, 0x300, v135
	s_waitcnt lgkmcnt(0)
	ds_write2st64_b32 v130, v132, v131 offset0:4 offset1:5
	s_bcnt1_i32_b64 s0, s[80:81]
	s_add_i32 s77, s77, s0
	s_mov_b64 exec, -1
	s_branch .Lnsel_nc_12
.Lnsel_c_13:
	s_mov_b64 exec, s[80:81]
	ds_read_b32 v132, v146 offset:3328
	v_mbcnt_lo_u32_b32 v130, s80, 0
	v_mbcnt_hi_u32_b32 v130, s81, v130
	v_add_u32_e32 v130, s77, v130
	v_lshl_add_u32 v130, v130, 2, s10
	v_add_u32_e32 v131, 0x340, v135
	s_waitcnt lgkmcnt(0)
	ds_write2st64_b32 v130, v132, v131 offset0:4 offset1:5
	s_bcnt1_i32_b64 s0, s[80:81]
	s_add_i32 s77, s77, s0
	s_mov_b64 exec, -1
	s_branch .Lnsel_nc_13
; __device__ __forceinline__ bool select_mask_fast(const LAS float* row, int nv, int ksel, LAS unsigned* scr, int lane, u64& word_o) {
;     ...
;     for (int j = 0; j < R - 1; ++j) { const int key = 64 * j + lane; const float v = row[key]; int bin = (int)fmaf(v, scale, nls); bin = bin > 255 ? 255 : bin; bin = bin < 0 ? 0 : bin; const bool in = v >= lo;
;         const u64 wd = __ballot(in && bin > B); if (lane == j) myword = wd;
;         if (in && bin == B) { const unsigned slot = __hip_atomic_fetch_add(&cnt[0], 1u, __ATOMIC_RELAXED, __HIP_MEMORY_SCOPE_WORKGROUP); if (slot < 64u) { candv[slot] = v; candi[slot] = key; } } }
;     { const int j = R - 1, key = 64 * j + lane; const float v = row[key]; const bool valid = key < nv && v >= lo; int bin = (int)fmaf(v, scale, nls); bin = bin > 255 ? 255 : bin; bin = bin < 0 ? 0 : bin;
;         const u64 wd = __ballot(valid && bin > B); if (lane == j) myword = wd;
;         if (valid && bin == B) { const unsigned slot = __hip_atomic_fetch_add(&cnt[0], 1u, __ATOMIC_RELAXED, __HIP_MEMORY_SCOPE_WORKGROUP); if (slot < 64u) { candv[slot] = v; candi[slot] = key; } } }
.Lnsel_c_14:
	s_mov_b64 exec, s[80:81]
	ds_read_b32 v132, v146 offset:3584
	v_mbcnt_lo_u32_b32 v130, s80, 0
	v_mbcnt_hi_u32_b32 v130, s81, v130
	v_add_u32_e32 v130, s77, v130
	v_lshl_add_u32 v130, v130, 2, s10
	v_add_u32_e32 v131, 0x380, v135
	s_waitcnt lgkmcnt(0)
	ds_write2st64_b32 v130, v132, v131 offset0:4 offset1:5
	s_bcnt1_i32_b64 s0, s[80:81]
	s_add_i32 s77, s77, s0
	s_mov_b64 exec, -1
	s_branch .Lnsel_nc_14
.Lnsel_c_15:
	s_mov_b64 exec, s[80:81]
	ds_read_b32 v132, v146 offset:3840
	v_mbcnt_lo_u32_b32 v130, s80, 0
	v_mbcnt_hi_u32_b32 v130, s81, v130
	v_add_u32_e32 v130, s77, v130
	v_lshl_add_u32 v130, v130, 2, s10
	v_add_u32_e32 v131, 0x3c0, v135
	s_waitcnt lgkmcnt(0)
	ds_write2st64_b32 v130, v132, v131 offset0:4 offset1:5
	s_bcnt1_i32_b64 s0, s[80:81]
	s_add_i32 s77, s77, s0
	s_mov_b64 exec, -1
	s_branch .Lnsel_nc_15
.Lnsel_c_16:
	s_mov_b64 exec, s[80:81]
	ds_read_b32 v132, v146 offset:4096
	v_mbcnt_lo_u32_b32 v130, s80, 0
	v_mbcnt_hi_u32_b32 v130, s81, v130
	v_add_u32_e32 v130, s77, v130
	v_lshl_add_u32 v130, v130, 2, s10
	v_add_u32_e32 v131, 0x400, v135
	s_waitcnt lgkmcnt(0)
	ds_write2st64_b32 v130, v132, v131 offset0:4 offset1:5
	s_bcnt1_i32_b64 s0, s[80:81]
	s_add_i32 s77, s77, s0
	s_mov_b64 exec, -1
	s_branch .Lnsel_nc_16
.Lnsel_c_17:
	s_mov_b64 exec, s[80:81]
	ds_read_b32 v132, v146 offset:4352
	v_mbcnt_lo_u32_b32 v130, s80, 0
	v_mbcnt_hi_u32_b32 v130, s81, v130
	v_add_u32_e32 v130, s77, v130
	v_lshl_add_u32 v130, v130, 2, s10
	v_add_u32_e32 v131, 0x440, v135
	s_waitcnt lgkmcnt(0)
	ds_write2st64_b32 v130, v132, v131 offset0:4 offset1:5
	s_bcnt1_i32_b64 s0, s[80:81]
	s_add_i32 s77, s77, s0
	s_mov_b64 exec, -1
	s_branch .Lnsel_nc_17
.Lnsel_c_18:
	s_mov_b64 exec, s[80:81]
	ds_read_b32 v132, v146 offset:4608
	v_mbcnt_lo_u32_b32 v130, s80, 0
	v_mbcnt_hi_u32_b32 v130, s81, v130
	v_add_u32_e32 v130, s77, v130
	v_lshl_add_u32 v130, v130, 2, s10
	v_add_u32_e32 v131, 0x480, v135
	s_waitcnt lgkmcnt(0)
	ds_write2st64_b32 v130, v132, v131 offset0:4 offset1:5
	s_bcnt1_i32_b64 s0, s[80:81]
	s_add_i32 s77, s77, s0
	s_mov_b64 exec, -1
	s_branch .Lnsel_nc_18
.Lnsel_c_19:
	s_mov_b64 exec, s[80:81]
	ds_read_b32 v132, v146 offset:4864
	v_mbcnt_lo_u32_b32 v130, s80, 0
	v_mbcnt_hi_u32_b32 v130, s81, v130
	v_add_u32_e32 v130, s77, v130
	v_lshl_add_u32 v130, v130, 2, s10
	v_add_u32_e32 v131, 0x4c0, v135
	s_waitcnt lgkmcnt(0)
	ds_write2st64_b32 v130, v132, v131 offset0:4 offset1:5
	s_bcnt1_i32_b64 s0, s[80:81]
	s_add_i32 s77, s77, s0
	s_mov_b64 exec, -1
	s_branch .Lnsel_nc_19
.Lnsel_c_20:
	s_mov_b64 exec, s[80:81]
	ds_read_b32 v132, v146 offset:5120
	v_mbcnt_lo_u32_b32 v130, s80, 0
	v_mbcnt_hi_u32_b32 v130, s81, v130
	v_add_u32_e32 v130, s77, v130
	v_lshl_add_u32 v130, v130, 2, s10
	v_add_u32_e32 v131, 0x500, v135
	s_waitcnt lgkmcnt(0)
	ds_write2st64_b32 v130, v132, v131 offset0:4 offset1:5
	s_bcnt1_i32_b64 s0, s[80:81]
	s_add_i32 s77, s77, s0
	s_mov_b64 exec, -1
	s_branch .Lnsel_nc_20
.Lnsel_c_21:
	s_mov_b64 exec, s[80:81]
	ds_read_b32 v132, v146 offset:5376
	v_mbcnt_lo_u32_b32 v130, s80, 0
	v_mbcnt_hi_u32_b32 v130, s81, v130
	v_add_u32_e32 v130, s77, v130
	v_lshl_add_u32 v130, v130, 2, s10
	v_add_u32_e32 v131, 0x540, v135
	s_waitcnt lgkmcnt(0)
	ds_write2st64_b32 v130, v132, v131 offset0:4 offset1:5
	s_bcnt1_i32_b64 s0, s[80:81]
	s_add_i32 s77, s77, s0
	s_mov_b64 exec, -1
	s_branch .Lnsel_nc_21
.Lnsel_c_22:
	s_mov_b64 exec, s[80:81]
	ds_read_b32 v132, v146 offset:5632
	v_mbcnt_lo_u32_b32 v130, s80, 0
	v_mbcnt_hi_u32_b32 v130, s81, v130
	v_add_u32_e32 v130, s77, v130
	v_lshl_add_u32 v130, v130, 2, s10
	v_add_u32_e32 v131, 0x580, v135
	s_waitcnt lgkmcnt(0)
	ds_write2st64_b32 v130, v132, v131 offset0:4 offset1:5
	s_bcnt1_i32_b64 s0, s[80:81]
	s_add_i32 s77, s77, s0
	s_mov_b64 exec, -1
	s_branch .Lnsel_nc_22
.Lnsel_c_23:
	s_mov_b64 exec, s[80:81]
	ds_read_b32 v132, v146 offset:5888
	v_mbcnt_lo_u32_b32 v130, s80, 0
	v_mbcnt_hi_u32_b32 v130, s81, v130
	v_add_u32_e32 v130, s77, v130
	v_lshl_add_u32 v130, v130, 2, s10
	v_add_u32_e32 v131, 0x5c0, v135
	s_waitcnt lgkmcnt(0)
	ds_write2st64_b32 v130, v132, v131 offset0:4 offset1:5
	s_bcnt1_i32_b64 s0, s[80:81]
	s_add_i32 s77, s77, s0
	s_mov_b64 exec, -1
	s_branch .Lnsel_nc_23
.Lnsel_c_24:
	s_mov_b64 exec, s[80:81]
	ds_read_b32 v132, v146 offset:6144
	v_mbcnt_lo_u32_b32 v130, s80, 0
	v_mbcnt_hi_u32_b32 v130, s81, v130
	v_add_u32_e32 v130, s77, v130
	v_lshl_add_u32 v130, v130, 2, s10
	v_add_u32_e32 v131, 0x600, v135
	s_waitcnt lgkmcnt(0)
	ds_write2st64_b32 v130, v132, v131 offset0:4 offset1:5
	s_bcnt1_i32_b64 s0, s[80:81]
	s_add_i32 s77, s77, s0
	s_mov_b64 exec, -1
	s_branch .Lnsel_nc_24
.Lnsel_c_25:
	s_mov_b64 exec, s[80:81]
	ds_read_b32 v132, v146 offset:6400
	v_mbcnt_lo_u32_b32 v130, s80, 0
	v_mbcnt_hi_u32_b32 v130, s81, v130
	v_add_u32_e32 v130, s77, v130
	v_lshl_add_u32 v130, v130, 2, s10
	v_add_u32_e32 v131, 0x640, v135
	s_waitcnt lgkmcnt(0)
	ds_write2st64_b32 v130, v132, v131 offset0:4 offset1:5
	s_bcnt1_i32_b64 s0, s[80:81]
	s_add_i32 s77, s77, s0
	s_mov_b64 exec, -1
	s_branch .Lnsel_nc_25
.Lnsel_c_26:
	s_mov_b64 exec, s[80:81]
	ds_read_b32 v132, v146 offset:6656
	v_mbcnt_lo_u32_b32 v130, s80, 0
	v_mbcnt_hi_u32_b32 v130, s81, v130
	v_add_u32_e32 v130, s77, v130
	v_lshl_add_u32 v130, v130, 2, s10
	v_add_u32_e32 v131, 0x680, v135
	s_waitcnt lgkmcnt(0)
	ds_write2st64_b32 v130, v132, v131 offset0:4 offset1:5
	s_bcnt1_i32_b64 s0, s[80:81]
	s_add_i32 s77, s77, s0
	s_mov_b64 exec, -1
	s_branch .Lnsel_nc_26
; __device__ __forceinline__ bool select_mask_fast(const LAS float* row, int nv, int ksel, LAS unsigned* scr, int lane, u64& word_o) {
;     ...
;     for (int j = 0; j < R - 1; ++j) { const int key = 64 * j + lane; const float v = row[key]; int bin = (int)fmaf(v, scale, nls); bin = bin > 255 ? 255 : bin; bin = bin < 0 ? 0 : bin; const bool in = v >= lo;
;         const u64 wd = __ballot(in && bin > B); if (lane == j) myword = wd;
;         if (in && bin == B) { const unsigned slot = __hip_atomic_fetch_add(&cnt[0], 1u, __ATOMIC_RELAXED, __HIP_MEMORY_SCOPE_WORKGROUP); if (slot < 64u) { candv[slot] = v; candi[slot] = key; } } }
;     { const int j = R - 1, key = 64 * j + lane; const float v = row[key]; const bool valid = key < nv && v >= lo; int bin = (int)fmaf(v, scale, nls); bin = bin > 255 ? 255 : bin; bin = bin < 0 ? 0 : bin;
;         const u64 wd = __ballot(valid && bin > B); if (lane == j) myword = wd;
;         if (valid && bin == B) { const unsigned slot = __hip_atomic_fetch_add(&cnt[0], 1u, __ATOMIC_RELAXED, __HIP_MEMORY_SCOPE_WORKGROUP); if (slot < 64u) { candv[slot] = v; candi[slot] = key; } } }
.Lnsel_c_27:
	s_mov_b64 exec, s[80:81]
	ds_read_b32 v132, v146 offset:6912
	v_mbcnt_lo_u32_b32 v130, s80, 0
	v_mbcnt_hi_u32_b32 v130, s81, v130
	v_add_u32_e32 v130, s77, v130
	v_lshl_add_u32 v130, v130, 2, s10
	v_add_u32_e32 v131, 0x6c0, v135
	s_waitcnt lgkmcnt(0)
	ds_write2st64_b32 v130, v132, v131 offset0:4 offset1:5
	s_bcnt1_i32_b64 s0, s[80:81]
	s_add_i32 s77, s77, s0
	s_mov_b64 exec, -1
	s_branch .Lnsel_nc_27
.Lnsel_c_28:
	s_mov_b64 exec, s[80:81]
	ds_read_b32 v132, v146 offset:7168
	v_mbcnt_lo_u32_b32 v130, s80, 0
	v_mbcnt_hi_u32_b32 v130, s81, v130
	v_add_u32_e32 v130, s77, v130
	v_lshl_add_u32 v130, v130, 2, s10
	v_add_u32_e32 v131, 0x700, v135
	s_waitcnt lgkmcnt(0)
	ds_write2st64_b32 v130, v132, v131 offset0:4 offset1:5
	s_bcnt1_i32_b64 s0, s[80:81]
	s_add_i32 s77, s77, s0
	s_mov_b64 exec, -1
	s_branch .Lnsel_nc_28
.Lnsel_c_29:
	s_mov_b64 exec, s[80:81]
	ds_read_b32 v132, v146 offset:7424
	v_mbcnt_lo_u32_b32 v130, s80, 0
	v_mbcnt_hi_u32_b32 v130, s81, v130
	v_add_u32_e32 v130, s77, v130
	v_lshl_add_u32 v130, v130, 2, s10
	v_add_u32_e32 v131, 0x740, v135
	s_waitcnt lgkmcnt(0)
	ds_write2st64_b32 v130, v132, v131 offset0:4 offset1:5
	s_bcnt1_i32_b64 s0, s[80:81]
	s_add_i32 s77, s77, s0
	s_mov_b64 exec, -1
	s_branch .Lnsel_nc_29
.Lnsel_c_30:
	s_mov_b64 exec, s[80:81]
	ds_read_b32 v132, v146 offset:7680
	v_mbcnt_lo_u32_b32 v130, s80, 0
	v_mbcnt_hi_u32_b32 v130, s81, v130
	v_add_u32_e32 v130, s77, v130
	v_lshl_add_u32 v130, v130, 2, s10
	v_add_u32_e32 v131, 0x780, v135
	s_waitcnt lgkmcnt(0)
	ds_write2st64_b32 v130, v132, v131 offset0:4 offset1:5
	s_bcnt1_i32_b64 s0, s[80:81]
	s_add_i32 s77, s77, s0
	s_mov_b64 exec, -1
	s_branch .Lnsel_nc_30
.Lnsel_c_31:
	s_mov_b64 exec, s[80:81]
	ds_read_b32 v132, v146 offset:7936
	v_mbcnt_lo_u32_b32 v130, s80, 0
	v_mbcnt_hi_u32_b32 v130, s81, v130
	v_add_u32_e32 v130, s77, v130
	v_lshl_add_u32 v130, v130, 2, s10
	v_add_u32_e32 v131, 0x7c0, v135
	s_waitcnt lgkmcnt(0)
	ds_write2st64_b32 v130, v132, v131 offset0:4 offset1:5
	s_bcnt1_i32_b64 s0, s[80:81]
	s_add_i32 s77, s77, s0
	s_mov_b64 exec, -1
	s_branch .Lnsel_nc_31
.Lnsel_c_32:
	s_mov_b64 exec, s[80:81]
	ds_read_b32 v132, v146 offset:8192
	v_mbcnt_lo_u32_b32 v130, s80, 0
	v_mbcnt_hi_u32_b32 v130, s81, v130
	v_add_u32_e32 v130, s77, v130
	v_lshl_add_u32 v130, v130, 2, s10
	v_add_u32_e32 v131, 0x800, v135
	s_waitcnt lgkmcnt(0)
	ds_write2st64_b32 v130, v132, v131 offset0:4 offset1:5
	s_bcnt1_i32_b64 s0, s[80:81]
	s_add_i32 s77, s77, s0
	s_mov_b64 exec, -1
	s_branch .Lnsel_nc_32
.Lnsel_c_33:
	s_mov_b64 exec, s[80:81]
	ds_read_b32 v132, v146 offset:8448
	v_mbcnt_lo_u32_b32 v130, s80, 0
	v_mbcnt_hi_u32_b32 v130, s81, v130
	v_add_u32_e32 v130, s77, v130
	v_lshl_add_u32 v130, v130, 2, s10
	v_add_u32_e32 v131, 0x840, v135
	s_waitcnt lgkmcnt(0)
	ds_write2st64_b32 v130, v132, v131 offset0:4 offset1:5
	s_bcnt1_i32_b64 s0, s[80:81]
	s_add_i32 s77, s77, s0
	s_mov_b64 exec, -1
	s_branch .Lnsel_nc_33
.Lnsel_c_34:
	s_mov_b64 exec, s[80:81]
	ds_read_b32 v132, v146 offset:8704
	v_mbcnt_lo_u32_b32 v130, s80, 0
	v_mbcnt_hi_u32_b32 v130, s81, v130
	v_add_u32_e32 v130, s77, v130
	v_lshl_add_u32 v130, v130, 2, s10
	v_add_u32_e32 v131, 0x880, v135
	s_waitcnt lgkmcnt(0)
	ds_write2st64_b32 v130, v132, v131 offset0:4 offset1:5
	s_bcnt1_i32_b64 s0, s[80:81]
	s_add_i32 s77, s77, s0
	s_mov_b64 exec, -1
	s_branch .Lnsel_nc_34
.Lnsel_c_35:
	s_mov_b64 exec, s[80:81]
	ds_read_b32 v132, v146 offset:8960
	v_mbcnt_lo_u32_b32 v130, s80, 0
	v_mbcnt_hi_u32_b32 v130, s81, v130
	v_add_u32_e32 v130, s77, v130
	v_lshl_add_u32 v130, v130, 2, s10
	v_add_u32_e32 v131, 0x8c0, v135
	s_waitcnt lgkmcnt(0)
	ds_write2st64_b32 v130, v132, v131 offset0:4 offset1:5
	s_bcnt1_i32_b64 s0, s[80:81]
	s_add_i32 s77, s77, s0
	s_mov_b64 exec, -1
	s_branch .Lnsel_nc_35
.Lnsel_c_36:
	s_mov_b64 exec, s[80:81]
	ds_read_b32 v132, v146 offset:9216
	v_mbcnt_lo_u32_b32 v130, s80, 0
	v_mbcnt_hi_u32_b32 v130, s81, v130
	v_add_u32_e32 v130, s77, v130
	v_lshl_add_u32 v130, v130, 2, s10
	v_add_u32_e32 v131, 0x900, v135
	s_waitcnt lgkmcnt(0)
	ds_write2st64_b32 v130, v132, v131 offset0:4 offset1:5
	s_bcnt1_i32_b64 s0, s[80:81]
	s_add_i32 s77, s77, s0
	s_mov_b64 exec, -1
	s_branch .Lnsel_nc_36
.Lnsel_c_37:
	s_mov_b64 exec, s[80:81]
	ds_read_b32 v132, v146 offset:9472
	v_mbcnt_lo_u32_b32 v130, s80, 0
	v_mbcnt_hi_u32_b32 v130, s81, v130
	v_add_u32_e32 v130, s77, v130
	v_lshl_add_u32 v130, v130, 2, s10
	v_add_u32_e32 v131, 0x940, v135
	s_waitcnt lgkmcnt(0)
	ds_write2st64_b32 v130, v132, v131 offset0:4 offset1:5
	s_bcnt1_i32_b64 s0, s[80:81]
	s_add_i32 s77, s77, s0
	s_mov_b64 exec, -1
	s_branch .Lnsel_nc_37
.Lnsel_c_38:
	s_mov_b64 exec, s[80:81]
	ds_read_b32 v132, v146 offset:9728
	v_mbcnt_lo_u32_b32 v130, s80, 0
	v_mbcnt_hi_u32_b32 v130, s81, v130
	v_add_u32_e32 v130, s77, v130
	v_lshl_add_u32 v130, v130, 2, s10
	v_add_u32_e32 v131, 0x980, v135
	s_waitcnt lgkmcnt(0)
	ds_write2st64_b32 v130, v132, v131 offset0:4 offset1:5
	s_bcnt1_i32_b64 s0, s[80:81]
	s_add_i32 s77, s77, s0
	s_mov_b64 exec, -1
	s_branch .Lnsel_nc_38
.Lnsel_c_39:
	s_mov_b64 exec, s[80:81]
	ds_read_b32 v132, v146 offset:9984
	v_mbcnt_lo_u32_b32 v130, s80, 0
	v_mbcnt_hi_u32_b32 v130, s81, v130
	v_add_u32_e32 v130, s77, v130
	v_lshl_add_u32 v130, v130, 2, s10
	v_add_u32_e32 v131, 0x9c0, v135
	s_waitcnt lgkmcnt(0)
	ds_write2st64_b32 v130, v132, v131 offset0:4 offset1:5
	s_bcnt1_i32_b64 s0, s[80:81]
	s_add_i32 s77, s77, s0
	s_mov_b64 exec, -1
	s_branch .Lnsel_nc_39
; __device__ __forceinline__ bool select_mask_fast(const LAS float* row, int nv, int ksel, LAS unsigned* scr, int lane, u64& word_o) {
;     ...
;     for (int j = 0; j < R - 1; ++j) { const int key = 64 * j + lane; const float v = row[key]; int bin = (int)fmaf(v, scale, nls); bin = bin > 255 ? 255 : bin; bin = bin < 0 ? 0 : bin; const bool in = v >= lo;
;         const u64 wd = __ballot(in && bin > B); if (lane == j) myword = wd;
;         if (in && bin == B) { const unsigned slot = __hip_atomic_fetch_add(&cnt[0], 1u, __ATOMIC_RELAXED, __HIP_MEMORY_SCOPE_WORKGROUP); if (slot < 64u) { candv[slot] = v; candi[slot] = key; } } }
;     { const int j = R - 1, key = 64 * j + lane; const float v = row[key]; const bool valid = key < nv && v >= lo; int bin = (int)fmaf(v, scale, nls); bin = bin > 255 ? 255 : bin; bin = bin < 0 ? 0 : bin;
;         const u64 wd = __ballot(valid && bin > B); if (lane == j) myword = wd;
;         if (valid && bin == B) { const unsigned slot = __hip_atomic_fetch_add(&cnt[0], 1u, __ATOMIC_RELAXED, __HIP_MEMORY_SCOPE_WORKGROUP); if (slot < 64u) { candv[slot] = v; candi[slot] = key; } } }
.Lnsel_c_40:
	s_mov_b64 exec, s[80:81]
	ds_read_b32 v132, v146 offset:10240
	v_mbcnt_lo_u32_b32 v130, s80, 0
	v_mbcnt_hi_u32_b32 v130, s81, v130
	v_add_u32_e32 v130, s77, v130
	v_lshl_add_u32 v130, v130, 2, s10
	v_add_u32_e32 v131, 0xa00, v135
	s_waitcnt lgkmcnt(0)
	ds_write2st64_b32 v130, v132, v131 offset0:4 offset1:5
	s_bcnt1_i32_b64 s0, s[80:81]
	s_add_i32 s77, s77, s0
	s_mov_b64 exec, -1
	s_branch .Lnsel_nc_40
.Lnsel_c_41:
	s_mov_b64 exec, s[80:81]
	ds_read_b32 v132, v146 offset:10496
	v_mbcnt_lo_u32_b32 v130, s80, 0
	v_mbcnt_hi_u32_b32 v130, s81, v130
	v_add_u32_e32 v130, s77, v130
	v_lshl_add_u32 v130, v130, 2, s10
	v_add_u32_e32 v131, 0xa40, v135
	s_waitcnt lgkmcnt(0)
	ds_write2st64_b32 v130, v132, v131 offset0:4 offset1:5
	s_bcnt1_i32_b64 s0, s[80:81]
	s_add_i32 s77, s77, s0
	s_mov_b64 exec, -1
	s_branch .Lnsel_nc_41
.Lnsel_c_42:
	s_mov_b64 exec, s[80:81]
	ds_read_b32 v132, v146 offset:10752
	v_mbcnt_lo_u32_b32 v130, s80, 0
	v_mbcnt_hi_u32_b32 v130, s81, v130
	v_add_u32_e32 v130, s77, v130
	v_lshl_add_u32 v130, v130, 2, s10
	v_add_u32_e32 v131, 0xa80, v135
	s_waitcnt lgkmcnt(0)
	ds_write2st64_b32 v130, v132, v131 offset0:4 offset1:5
	s_bcnt1_i32_b64 s0, s[80:81]
	s_add_i32 s77, s77, s0
	s_mov_b64 exec, -1
	s_branch .Lnsel_nc_42
.Lnsel_c_43:
	s_mov_b64 exec, s[80:81]
	ds_read_b32 v132, v146 offset:11008
	v_mbcnt_lo_u32_b32 v130, s80, 0
	v_mbcnt_hi_u32_b32 v130, s81, v130
	v_add_u32_e32 v130, s77, v130
	v_lshl_add_u32 v130, v130, 2, s10
	v_add_u32_e32 v131, 0xac0, v135
	s_waitcnt lgkmcnt(0)
	ds_write2st64_b32 v130, v132, v131 offset0:4 offset1:5
	s_bcnt1_i32_b64 s0, s[80:81]
	s_add_i32 s77, s77, s0
	s_mov_b64 exec, -1
	s_branch .Lnsel_nc_43
.Lnsel_c_44:
	s_mov_b64 exec, s[80:81]
	ds_read_b32 v132, v146 offset:11264
	v_mbcnt_lo_u32_b32 v130, s80, 0
	v_mbcnt_hi_u32_b32 v130, s81, v130
	v_add_u32_e32 v130, s77, v130
	v_lshl_add_u32 v130, v130, 2, s10
	v_add_u32_e32 v131, 0xb00, v135
	s_waitcnt lgkmcnt(0)
	ds_write2st64_b32 v130, v132, v131 offset0:4 offset1:5
	s_bcnt1_i32_b64 s0, s[80:81]
	s_add_i32 s77, s77, s0
	s_mov_b64 exec, -1
	s_branch .Lnsel_nc_44
.Lnsel_c_45:
	s_mov_b64 exec, s[80:81]
	ds_read_b32 v132, v146 offset:11520
	v_mbcnt_lo_u32_b32 v130, s80, 0
	v_mbcnt_hi_u32_b32 v130, s81, v130
	v_add_u32_e32 v130, s77, v130
	v_lshl_add_u32 v130, v130, 2, s10
	v_add_u32_e32 v131, 0xb40, v135
	s_waitcnt lgkmcnt(0)
	ds_write2st64_b32 v130, v132, v131 offset0:4 offset1:5
	s_bcnt1_i32_b64 s0, s[80:81]
	s_add_i32 s77, s77, s0
	s_mov_b64 exec, -1
	s_branch .Lnsel_nc_45
.Lnsel_c_46:
	s_mov_b64 exec, s[80:81]
	ds_read_b32 v132, v146 offset:11776
	v_mbcnt_lo_u32_b32 v130, s80, 0
	v_mbcnt_hi_u32_b32 v130, s81, v130
	v_add_u32_e32 v130, s77, v130
	v_lshl_add_u32 v130, v130, 2, s10
	v_add_u32_e32 v131, 0xb80, v135
	s_waitcnt lgkmcnt(0)
	ds_write2st64_b32 v130, v132, v131 offset0:4 offset1:5
	s_bcnt1_i32_b64 s0, s[80:81]
	s_add_i32 s77, s77, s0
	s_mov_b64 exec, -1
	s_branch .Lnsel_nc_46
.Lnsel_c_47:
	s_mov_b64 exec, s[80:81]
	ds_read_b32 v132, v146 offset:12032
	v_mbcnt_lo_u32_b32 v130, s80, 0
	v_mbcnt_hi_u32_b32 v130, s81, v130
	v_add_u32_e32 v130, s77, v130
	v_lshl_add_u32 v130, v130, 2, s10
	v_add_u32_e32 v131, 0xbc0, v135
	s_waitcnt lgkmcnt(0)
	ds_write2st64_b32 v130, v132, v131 offset0:4 offset1:5
	s_bcnt1_i32_b64 s0, s[80:81]
	s_add_i32 s77, s77, s0
	s_mov_b64 exec, -1
	s_branch .Lnsel_nc_47
.Lnsel_c_48:
	s_mov_b64 exec, s[80:81]
	ds_read_b32 v132, v146 offset:12288
	v_mbcnt_lo_u32_b32 v130, s80, 0
	v_mbcnt_hi_u32_b32 v130, s81, v130
	v_add_u32_e32 v130, s77, v130
	v_lshl_add_u32 v130, v130, 2, s10
	v_add_u32_e32 v131, 0xc00, v135
	s_waitcnt lgkmcnt(0)
	ds_write2st64_b32 v130, v132, v131 offset0:4 offset1:5
	s_bcnt1_i32_b64 s0, s[80:81]
	s_add_i32 s77, s77, s0
	s_mov_b64 exec, -1
	s_branch .Lnsel_nc_48
.Lnsel_c_49:
	s_mov_b64 exec, s[80:81]
	ds_read_b32 v132, v146 offset:12544
	v_mbcnt_lo_u32_b32 v130, s80, 0
	v_mbcnt_hi_u32_b32 v130, s81, v130
	v_add_u32_e32 v130, s77, v130
	v_lshl_add_u32 v130, v130, 2, s10
	v_add_u32_e32 v131, 0xc40, v135
	s_waitcnt lgkmcnt(0)
	ds_write2st64_b32 v130, v132, v131 offset0:4 offset1:5
	s_bcnt1_i32_b64 s0, s[80:81]
	s_add_i32 s77, s77, s0
	s_mov_b64 exec, -1
	s_branch .Lnsel_nc_49
.Lnsel_c_50:
	s_mov_b64 exec, s[80:81]
	ds_read_b32 v132, v146 offset:12800
	v_mbcnt_lo_u32_b32 v130, s80, 0
	v_mbcnt_hi_u32_b32 v130, s81, v130
	v_add_u32_e32 v130, s77, v130
	v_lshl_add_u32 v130, v130, 2, s10
	v_add_u32_e32 v131, 0xc80, v135
	s_waitcnt lgkmcnt(0)
	ds_write2st64_b32 v130, v132, v131 offset0:4 offset1:5
	s_bcnt1_i32_b64 s0, s[80:81]
	s_add_i32 s77, s77, s0
	s_mov_b64 exec, -1
	s_branch .Lnsel_nc_50
.Lnsel_c_51:
	s_mov_b64 exec, s[80:81]
	ds_read_b32 v132, v146 offset:13056
	v_mbcnt_lo_u32_b32 v130, s80, 0
	v_mbcnt_hi_u32_b32 v130, s81, v130
	v_add_u32_e32 v130, s77, v130
	v_lshl_add_u32 v130, v130, 2, s10
	v_add_u32_e32 v131, 0xcc0, v135
	s_waitcnt lgkmcnt(0)
	ds_write2st64_b32 v130, v132, v131 offset0:4 offset1:5
	s_bcnt1_i32_b64 s0, s[80:81]
	s_add_i32 s77, s77, s0
	s_mov_b64 exec, -1
	s_branch .Lnsel_nc_51
; #define SMF_FOR(...) { _Pragma("unroll 4") for (int j = 0; j < R - 1; ++j) { const int key = 64 * j + lane; const float v = row[key]; (void)key; __VA_ARGS__ } \
;                        { const int key = 64 * (R - 1) + lane; if (key < nv) { const float v = row[key]; __VA_ARGS__ } } }
; __device__ __forceinline__ bool select_mask_fast(const LAS float* row, int nv, int ksel, LAS unsigned* scr, int lane, u64& word_o) {
;     ...
;     float m0 = -INFINITY, m1 = -INFINITY, m2 = -INFINITY, m3 = -INFINITY;
;     SMF_FOR({ const float n1 = __builtin_amdgcn_fmed3f(m0, m1, v), n2 = __builtin_amdgcn_fmed3f(m1, m2, v), n3 = __builtin_amdgcn_fmed3f(m2, m3, v); m0 = __builtin_amdgcn_fmed3f(m0, v, BIGF); m1 = n1; m2 = n2; m3 = n3; })
;     ...
;     for (int j = 0; j < R - 1; ++j) { const int key = 64 * j + lane; const float v = row[key]; int bin = (int)fmaf(v, scale, nls); bin = bin > 255 ? 255 : bin; bin = bin < 0 ? 0 : bin; const bool in = v >= lo;
;         const u64 wd = __ballot(in && bin > B); if (lane == j) myword = wd;
;         if (in && bin == B) { const unsigned slot = __hip_atomic_fetch_add(&cnt[0], 1u, __ATOMIC_RELAXED, __HIP_MEMORY_SCOPE_WORKGROUP); if (slot < 64u) { candv[slot] = v; candi[slot] = key; } } }
;     { const int j = R - 1, key = 64 * j + lane; const float v = row[key]; const bool valid = key < nv && v >= lo; int bin = (int)fmaf(v, scale, nls); bin = bin > 255 ? 255 : bin; bin = bin < 0 ? 0 : bin;
;         const u64 wd = __ballot(valid && bin > B); if (lane == j) myword = wd;
;         if (valid && bin == B) { const unsigned slot = __hip_atomic_fetch_add(&cnt[0], 1u, __ATOMIC_RELAXED, __HIP_MEMORY_SCOPE_WORKGROUP); if (slot < 64u) { candv[slot] = v; candi[slot] = key; } } }
.Lnsel_c_52:
	s_mov_b64 exec, s[80:81]
	ds_read_b32 v132, v146 offset:13312
	v_mbcnt_lo_u32_b32 v130, s80, 0
	v_mbcnt_hi_u32_b32 v130, s81, v130
	v_add_u32_e32 v130, s77, v130
	v_lshl_add_u32 v130, v130, 2, s10
	v_add_u32_e32 v131, 0xd00, v135
	s_waitcnt lgkmcnt(0)
	ds_write2st64_b32 v130, v132, v131 offset0:4 offset1:5
	s_bcnt1_i32_b64 s0, s[80:81]
	s_add_i32 s77, s77, s0
	s_mov_b64 exec, -1
	s_branch .Lnsel_nc_52
.Lnsel_c_53:
	s_mov_b64 exec, s[80:81]
	ds_read_b32 v132, v146 offset:13568
	v_mbcnt_lo_u32_b32 v130, s80, 0
	v_mbcnt_hi_u32_b32 v130, s81, v130
	v_add_u32_e32 v130, s77, v130
	v_lshl_add_u32 v130, v130, 2, s10
	v_add_u32_e32 v131, 0xd40, v135
	s_waitcnt lgkmcnt(0)
	ds_write2st64_b32 v130, v132, v131 offset0:4 offset1:5
	s_bcnt1_i32_b64 s0, s[80:81]
	s_add_i32 s77, s77, s0
	s_mov_b64 exec, -1
	s_branch .Lnsel_nc_53
.Lnsel_c_54:
	s_mov_b64 exec, s[80:81]
	ds_read_b32 v132, v146 offset:13824
	v_mbcnt_lo_u32_b32 v130, s80, 0
	v_mbcnt_hi_u32_b32 v130, s81, v130
	v_add_u32_e32 v130, s77, v130
	v_lshl_add_u32 v130, v130, 2, s10
	v_add_u32_e32 v131, 0xd80, v135
	s_waitcnt lgkmcnt(0)
	ds_write2st64_b32 v130, v132, v131 offset0:4 offset1:5
	s_bcnt1_i32_b64 s0, s[80:81]
	s_add_i32 s77, s77, s0
	s_mov_b64 exec, -1
	s_branch .Lnsel_nc_54
.Lnsel_c_55:
	s_mov_b64 exec, s[80:81]
	ds_read_b32 v132, v146 offset:14080
	v_mbcnt_lo_u32_b32 v130, s80, 0
	v_mbcnt_hi_u32_b32 v130, s81, v130
	v_add_u32_e32 v130, s77, v130
	v_lshl_add_u32 v130, v130, 2, s10
	v_add_u32_e32 v131, 0xdc0, v135
	s_waitcnt lgkmcnt(0)
	ds_write2st64_b32 v130, v132, v131 offset0:4 offset1:5
	s_bcnt1_i32_b64 s0, s[80:81]
	s_add_i32 s77, s77, s0
	s_mov_b64 exec, -1
	s_branch .Lnsel_nc_55
.Lnsel_c_56:
	s_mov_b64 exec, s[80:81]
	ds_read_b32 v132, v146 offset:14336
	v_mbcnt_lo_u32_b32 v130, s80, 0
	v_mbcnt_hi_u32_b32 v130, s81, v130
	v_add_u32_e32 v130, s77, v130
	v_lshl_add_u32 v130, v130, 2, s10
	v_add_u32_e32 v131, 0xe00, v135
	s_waitcnt lgkmcnt(0)
	ds_write2st64_b32 v130, v132, v131 offset0:4 offset1:5
	s_bcnt1_i32_b64 s0, s[80:81]
	s_add_i32 s77, s77, s0
	s_mov_b64 exec, -1
	s_branch .Lnsel_nc_56
.Lnsel_c_57:
	s_mov_b64 exec, s[80:81]
	ds_read_b32 v132, v146 offset:14592
	v_mbcnt_lo_u32_b32 v130, s80, 0
	v_mbcnt_hi_u32_b32 v130, s81, v130
	v_add_u32_e32 v130, s77, v130
	v_lshl_add_u32 v130, v130, 2, s10
	v_add_u32_e32 v131, 0xe40, v135
	s_waitcnt lgkmcnt(0)
	ds_write2st64_b32 v130, v132, v131 offset0:4 offset1:5
	s_bcnt1_i32_b64 s0, s[80:81]
	s_add_i32 s77, s77, s0
	s_mov_b64 exec, -1
	s_branch .Lnsel_nc_57
.Lnsel_c_58:
	s_mov_b64 exec, s[80:81]
	ds_read_b32 v132, v146 offset:14848
	v_mbcnt_lo_u32_b32 v130, s80, 0
	v_mbcnt_hi_u32_b32 v130, s81, v130
	v_add_u32_e32 v130, s77, v130
	v_lshl_add_u32 v130, v130, 2, s10
	v_add_u32_e32 v131, 0xe80, v135
	s_waitcnt lgkmcnt(0)
	ds_write2st64_b32 v130, v132, v131 offset0:4 offset1:5
	s_bcnt1_i32_b64 s0, s[80:81]
	s_add_i32 s77, s77, s0
	s_mov_b64 exec, -1
	s_branch .Lnsel_nc_58
.Lnsel_c_59:
	s_mov_b64 exec, s[80:81]
	ds_read_b32 v132, v146 offset:15104
	v_mbcnt_lo_u32_b32 v130, s80, 0
	v_mbcnt_hi_u32_b32 v130, s81, v130
	v_add_u32_e32 v130, s77, v130
	v_lshl_add_u32 v130, v130, 2, s10
	v_add_u32_e32 v131, 0xec0, v135
	s_waitcnt lgkmcnt(0)
	ds_write2st64_b32 v130, v132, v131 offset0:4 offset1:5
	s_bcnt1_i32_b64 s0, s[80:81]
	s_add_i32 s77, s77, s0
	s_mov_b64 exec, -1
	s_branch .Lnsel_nc_59
.Lnsel_c_60:
	s_mov_b64 exec, s[80:81]
	ds_read_b32 v132, v146 offset:15360
	v_mbcnt_lo_u32_b32 v130, s80, 0
	v_mbcnt_hi_u32_b32 v130, s81, v130
	v_add_u32_e32 v130, s77, v130
	v_lshl_add_u32 v130, v130, 2, s10
	v_add_u32_e32 v131, 0xf00, v135
	s_waitcnt lgkmcnt(0)
	ds_write2st64_b32 v130, v132, v131 offset0:4 offset1:5
	s_bcnt1_i32_b64 s0, s[80:81]
	s_add_i32 s77, s77, s0
	s_mov_b64 exec, -1
	s_branch .Lnsel_nc_60
.Lnsel_c_61:
	s_mov_b64 exec, s[80:81]
	ds_read_b32 v132, v146 offset:15616
	v_mbcnt_lo_u32_b32 v130, s80, 0
	v_mbcnt_hi_u32_b32 v130, s81, v130
	v_add_u32_e32 v130, s77, v130
	v_lshl_add_u32 v130, v130, 2, s10
	v_add_u32_e32 v131, 0xf40, v135
	s_waitcnt lgkmcnt(0)
	ds_write2st64_b32 v130, v132, v131 offset0:4 offset1:5
	s_bcnt1_i32_b64 s0, s[80:81]
	s_add_i32 s77, s77, s0
	s_mov_b64 exec, -1
	s_branch .Lnsel_nc_61
.Lnsel_c_62:
	s_mov_b64 exec, s[80:81]
	ds_read_b32 v132, v146 offset:15872
	v_mbcnt_lo_u32_b32 v130, s80, 0
	v_mbcnt_hi_u32_b32 v130, s81, v130
	v_add_u32_e32 v130, s77, v130
	v_lshl_add_u32 v130, v130, 2, s10
	v_add_u32_e32 v131, 0xf80, v135
	s_waitcnt lgkmcnt(0)
	ds_write2st64_b32 v130, v132, v131 offset0:4 offset1:5
	s_bcnt1_i32_b64 s0, s[80:81]
	s_add_i32 s77, s77, s0
	s_mov_b64 exec, -1
	s_branch .Lnsel_nc_62
.Lnsel_c_63:
	s_mov_b64 exec, s[80:81]
	ds_read_b32 v132, v146 offset:16128
	v_mbcnt_lo_u32_b32 v130, s80, 0
	v_mbcnt_hi_u32_b32 v130, s81, v130
	v_add_u32_e32 v130, s77, v130
	v_lshl_add_u32 v130, v130, 2, s10
	v_add_u32_e32 v131, 0xfc0, v135
	s_waitcnt lgkmcnt(0)
	ds_write2st64_b32 v130, v132, v131 offset0:4 offset1:5
	s_bcnt1_i32_b64 s0, s[80:81]
	s_add_i32 s77, s77, s0
	s_mov_b64 exec, -1
	s_branch .Lnsel_nc_63
.Lnsel_bail:
	s_mov_b64 exec, -1
	s_waitcnt lgkmcnt(0)
	s_add_i32 s0, s52, 64
	s_lshr_b32 s53, s0, 6
	s_add_i32 s49, s53, -1
	s_add_i32 s0, s53, -2
	s_cmp_lt_u32 s0, 3
	s_cbranch_scc1 .LBB0_746
	s_and_b32 s0, s49, -4
	s_mov_b32 s1, 0
	v_mov_b32_e32 v130, 0xff800000
	v_mov_b32_e32 v144, v146
	v_mov_b32_e32 v133, 0xff800000
	v_mov_b32_e32 v132, 0xff800000
	v_mov_b32_e32 v131, 0xff800000
